# GEMM LDS stores of the next k-step interleaved between MFMA groups
# baseline (speedup 1.0000x reference)
; __device__ __forceinline__ void gemm_kstep(const u16* sb, int wn, int wt, int r, int h, f32x16 (&acc)[2][2]) {
;   const u16* bw = sb + (wn * 64 + r) * LDT + h * 8;
;   const u16* bx = sb + TILE_U16 + (wt * 64 + r) * LDT + h * 8;
;   __builtin_amdgcn_s_setprio(1);
; #pragma unroll
;   for (int ks = 0; ks < 4; ++ks) {
;     bf16x8 a0 = *(const bf16x8*)(bw + ks * 16);
;     bf16x8 a1 = *(const bf16x8*)(bw + 32 * LDT + ks * 16);
;     bf16x8 b0 = *(const bf16x8*)(bx + ks * 16);
;     bf16x8 b1 = *(const bf16x8*)(bx + 32 * LDT + ks * 16);
;     acc[0][0] = mfma32(a0, b0, acc[0][0]);
;     acc[0][1] = mfma32(a0, b1, acc[0][1]);
;     acc[1][0] = mfma32(a1, b0, acc[1][0]);
;     acc[1][1] = mfma32(a1, b1, acc[1][1]);
;   }
;   __builtin_amdgcn_s_setprio(0);
; }
; __device__ void gemm_phase(const u16* __restrict__ Wb, int ldw, const u16* __restrict__ Xb, int ldx, int K,
;                            u16* __restrict__ outb, int ldo, int ntn, int ntiles, u16* lds) {
;     ...
;   for (; q < L; q += nbl) {
;     const int qn = q + nbl;
;     const bool has_next = qn < L;
;     const int qq = has_next ? qn : q;
;     const u16* gwn = Wb + (size_t)(GP_NT(qq) * 128 + lrow) * ldw + lc * 8;
;     const u16* gxn = Xb + (size_t)(GP_MT(qq) * 128 + lrow) * ldx + lc * 8;
;     f32x16 acc[2][2];
; #pragma unroll
;     for (int a = 0; a < 2; ++a)
; #pragma unroll
;       for (int b = 0; b < 2; ++b)
; #pragma unroll
;         for (int i = 0; i < 16; ++i) acc[a][b][i] = 0.f;
;     gs_store(B, lds, lo);
;     __syncthreads();
;     for (int kt = 0; kt < nk; kt += 2) {
;       if (kt + 2 < nk) gs_load(B, gw, ldw, gx, ldx, (kt + 2) * 64);
;       else if (has_next) gs_load(B, gwn, ldw, gxn, ldx, 0);
;       gemm_kstep(lds, wn, wt, r, h, acc);
;       gs_store(A, lds + 2 * TILE_U16, lo);
;       __syncthreads();
.LBB0_598:
	v_mov_b64_e32 v[160:161], v[132:133]
	v_add_co_u32_e32 v162, vcc, s81, v160
	v_mov_b64_e32 v[158:159], v[134:135]
	s_nop 0
	v_addc_co_u32_e32 v163, vcc, 0, v161, vcc
	v_add_co_u32_e32 v164, vcc, s80, v160
	s_waitcnt vmcnt(1)
	ds_write_b128 v188, v[98:101]
	ds_write_b128 v188, v[102:105] offset:4608
	ds_write_b128 v188, v[106:109] offset:9216
	ds_write_b128 v188, v[110:113] offset:13824
	ds_write_b128 v188, v[114:117] offset:18432
	ds_write_b128 v188, v[118:121] offset:23040
	ds_write_b128 v188, v[122:125] offset:27648
	ds_write_b128 v188, v[126:129] offset:32256
	v_addc_co_u32_e32 v165, vcc, 0, v161, vcc
	v_add_co_u32_e32 v166, vcc, s84, v160
	s_waitcnt lgkmcnt(0)
	s_nop 0
	v_addc_co_u32_e32 v167, vcc, 0, v161, vcc
	v_add_co_u32_e32 v168, vcc, s81, v158
	s_barrier
	s_nop 0
	v_addc_co_u32_e32 v169, vcc, 0, v159, vcc
	v_add_co_u32_e32 v170, vcc, s80, v158
	s_nop 1
	v_addc_co_u32_e32 v171, vcc, 0, v159, vcc
	v_add_co_u32_e32 v172, vcc, s84, v158
	global_load_dwordx4 v[98:101], v[160:161], off offset:256
	global_load_dwordx4 v[102:105], v[162:163], off offset:256
	v_addc_co_u32_e32 v173, vcc, 0, v159, vcc
	global_load_dwordx4 v[106:109], v[164:165], off offset:256
	global_load_dwordx4 v[110:113], v[166:167], off offset:256
	global_load_dwordx4 v[114:117], v[158:159], off offset:256
	global_load_dwordx4 v[118:121], v[168:169], off offset:256
	global_load_dwordx4 v[122:125], v[170:171], off offset:256
	global_load_dwordx4 v[126:129], v[172:173], off offset:256
	s_add_i32 s38, s39, s87
	s_cmpk_gt_u32 s38, 0x23f
	s_cselect_b64 s[16:17], -1, 0
	s_cmpk_lt_u32 s38, 0x240
	s_cselect_b64 s[0:1], -1, 0
	s_and_b64 s[40:41], s[0:1], exec
	s_cselect_b32 s40, s38, s39
	s_mul_hi_u32 s41, s40, 0x38e38e39
	s_lshr_b32 s41, s41, 5
	s_mul_i32 s44, s41, 0x90
	s_sub_i32 s40, s40, s44
	s_lshl_b32 s44, s40, 4
	s_and_b32 s40, s40, 7
	s_or_b32 s40, s40, s18
	s_lshl_b32 s41, s41, 10
	s_lshl_b32 s40, s40, 7
	s_and_b32 s44, s44, 0xf80
	s_add_i32 s40, s40, s41
	v_add_u32_e32 v2, s44, v131
	v_add_u32_e32 v4, s40, v131
	v_ashrrev_i32_e32 v3, 31, v2
	v_ashrrev_i32_e32 v5, 31, v4
	v_lshlrev_b64 v[2:3], 11, v[2:3]
	v_lshlrev_b64 v[4:5], 11, v[4:5]
	v_lshl_add_u64 v[132:133], v[136:137], 0, v[2:3]
	v_lshl_add_u64 v[134:135], v[138:139], 0, v[4:5]
	s_setprio 1
	ds_read_b128 v[2:5], v140
	ds_read_b128 v[6:9], v141 offset:18432
	ds_read_b128 v[10:13], v141 offset:23040
	s_waitcnt lgkmcnt(1)
	v_mfma_f32_32x32x16_bf16 v[50:65], v[2:5], v[6:9], 0
	s_waitcnt lgkmcnt(0)
	v_mfma_f32_32x32x16_bf16 v[34:49], v[2:5], v[10:13], 0
	ds_read_b128 v[2:5], v140 offset:4608
	ds_read_b128 v[198:201], v140 offset:32
	ds_read_b128 v[202:205], v141 offset:18464
	ds_read_b128 v[206:209], v141 offset:23072
	s_waitcnt lgkmcnt(1)
	v_mfma_f32_32x32x16_bf16 v[50:65], v[198:201], v[202:205], v[50:65]
	s_waitcnt lgkmcnt(0)
	v_mfma_f32_32x32x16_bf16 v[34:49], v[198:201], v[206:209], v[34:49]
	ds_read_b128 v[198:201], v140 offset:4640
	v_mfma_f32_32x32x16_bf16 v[18:33], v[2:5], v[6:9], 0
	v_mfma_f32_32x32x16_bf16 v[2:17], v[2:5], v[10:13], 0
	s_waitcnt lgkmcnt(0)
	v_mfma_f32_32x32x16_bf16 v[18:33], v[198:201], v[202:205], v[18:33]
	v_mfma_f32_32x32x16_bf16 v[2:17], v[198:201], v[206:209], v[2:17]
	ds_read_b128 v[198:201], v140 offset:64
	ds_read_b128 v[202:205], v141 offset:18496
	ds_read_b128 v[206:209], v141 offset:23104
	s_waitcnt lgkmcnt(1)
	v_mfma_f32_32x32x16_bf16 v[50:65], v[198:201], v[202:205], v[50:65]
	s_waitcnt lgkmcnt(0)
	v_mfma_f32_32x32x16_bf16 v[34:49], v[198:201], v[206:209], v[34:49]
	ds_read_b128 v[198:201], v140 offset:4672
	s_waitcnt lgkmcnt(0)
	v_mfma_f32_32x32x16_bf16 v[18:33], v[198:201], v[202:205], v[18:33]
	v_mfma_f32_32x32x16_bf16 v[2:17], v[198:201], v[206:209], v[2:17]
	ds_read_b128 v[198:201], v140 offset:96
	ds_read_b128 v[202:205], v141 offset:18528
	ds_read_b128 v[206:209], v141 offset:23136
	s_waitcnt lgkmcnt(1)
	v_mfma_f32_32x32x16_bf16 v[50:65], v[198:201], v[202:205], v[50:65]
	s_waitcnt lgkmcnt(0)
	v_mfma_f32_32x32x16_bf16 v[34:49], v[198:201], v[206:209], v[34:49]
	ds_read_b128 v[198:201], v140 offset:4704
	s_waitcnt lgkmcnt(0)
	v_mfma_f32_32x32x16_bf16 v[18:33], v[198:201], v[202:205], v[18:33]
	v_mfma_f32_32x32x16_bf16 v[2:17], v[198:201], v[206:209], v[2:17]
	s_setprio 0
	ds_write_b128 v188, v[66:69] offset:36864
	ds_write_b128 v188, v[70:73] offset:41472
	ds_write_b128 v188, v[74:77] offset:46080
	ds_write_b128 v188, v[78:81] offset:50688
	ds_write_b128 v188, v[82:85] offset:55296
	ds_write_b128 v188, v[86:89] offset:59904
	ds_write_b128 v188, v[90:93] offset:64512
	s_waitcnt vmcnt(8)
	ds_write_b128 v189, v[94:97] offset:13824
	s_waitcnt lgkmcnt(0)
	s_barrier
; __device__ __forceinline__ void gemm_kstep(const u16* sb, int wn, int wt, int r, int h, f32x16 (&acc)[2][2]) {
;   const u16* bw = sb + (wn * 64 + r) * LDT + h * 8;
;   const u16* bx = sb + TILE_U16 + (wt * 64 + r) * LDT + h * 8;
;   __builtin_amdgcn_s_setprio(1);
; #pragma unroll
;   for (int ks = 0; ks < 4; ++ks) {
;     bf16x8 a0 = *(const bf16x8*)(bw + ks * 16);
;     bf16x8 a1 = *(const bf16x8*)(bw + 32 * LDT + ks * 16);
;     bf16x8 b0 = *(const bf16x8*)(bx + ks * 16);
;     bf16x8 b1 = *(const bf16x8*)(bx + 32 * LDT + ks * 16);
;     acc[0][0] = mfma32(a0, b0, acc[0][0]);
;     acc[0][1] = mfma32(a0, b1, acc[0][1]);
;     acc[1][0] = mfma32(a1, b0, acc[1][0]);
;     acc[1][1] = mfma32(a1, b1, acc[1][1]);
;   }
;   __builtin_amdgcn_s_setprio(0);
; }
; __device__ void gemm_phase(const u16* __restrict__ Wb, int ldw, const u16* __restrict__ Xb, int ldx, int K,
;                            u16* __restrict__ outb, int ldo, int ntn, int ntiles, u16* lds) {
;     ...
;     for (int kt = 0; kt < nk; kt += 2) {
;       if (kt + 2 < nk) gs_load(B, gw, ldw, gx, ldx, (kt + 2) * 64);
;       else if (has_next) gs_load(B, gwn, ldw, gxn, ldx, 0);
;       gemm_kstep(lds, wn, wt, r, h, acc);
;       gs_store(A, lds + 2 * TILE_U16, lo);
;       __syncthreads();
;       if (kt + 3 < nk) gs_load(A, gw, ldw, gx, ldx, (kt + 3) * 64);
;       else if (has_next) gs_load(A, gwn, ldw, gxn, ldx, 64);
;       gemm_kstep(lds + 2 * TILE_U16, wn, wt, r, h, acc);
;       if (kt + 2 < nk) gs_store(B, lds, lo);
;       __syncthreads();
;     }
	s_setprio 1
	ds_read_b128 v[198:201], v140 offset:36864
	ds_read_b128 v[202:205], v141 offset:55296
	ds_read_b128 v[206:209], v141 offset:59904
	ds_read_b128 v[214:217], v140 offset:41472
	ds_read_b128 v[218:221], v140 offset:36896
	ds_read_b128 v[222:225], v141 offset:55328
	ds_read_b128 v[226:229], v141 offset:59936
	ds_read_b128 v[230:233], v140 offset:41504
	s_waitcnt lgkmcnt(4)
	v_mfma_f32_32x32x16_bf16 v[50:65], v[198:201], v[202:205], v[50:65]
	v_mfma_f32_32x32x16_bf16 v[34:49], v[198:201], v[206:209], v[34:49]
	v_mfma_f32_32x32x16_bf16 v[18:33], v[214:217], v[202:205], v[18:33]
	v_mfma_f32_32x32x16_bf16 v[2:17], v[214:217], v[206:209], v[2:17]
	global_load_dwordx4 v[66:69], v[160:161], off offset:384
	global_load_dwordx4 v[70:73], v[162:163], off offset:384
	global_load_dwordx4 v[74:77], v[164:165], off offset:384
	global_load_dwordx4 v[78:81], v[166:167], off offset:384
	global_load_dwordx4 v[82:85], v[158:159], off offset:384
	global_load_dwordx4 v[86:89], v[168:169], off offset:384
	global_load_dwordx4 v[90:93], v[170:171], off offset:384
	global_load_dwordx4 v[94:97], v[172:173], off offset:384
	ds_read_b128 v[198:201], v140 offset:36928
	ds_read_b128 v[202:205], v141 offset:55360
	ds_read_b128 v[206:209], v141 offset:59968
	ds_read_b128 v[214:217], v140 offset:41536
	s_waitcnt lgkmcnt(4)
	v_mfma_f32_32x32x16_bf16 v[50:65], v[218:221], v[222:225], v[50:65]
	v_mfma_f32_32x32x16_bf16 v[34:49], v[218:221], v[226:229], v[34:49]
	v_mfma_f32_32x32x16_bf16 v[18:33], v[230:233], v[222:225], v[18:33]
	v_mfma_f32_32x32x16_bf16 v[2:17], v[230:233], v[226:229], v[2:17]
	s_waitcnt vmcnt(8)
	ds_write_b128 v188, v[98:101]
	ds_write_b128 v188, v[102:105] offset:4608
	ds_write_b128 v188, v[106:109] offset:9216
	ds_write_b128 v188, v[110:113] offset:13824
	ds_read_b128 v[218:221], v140 offset:36960
	ds_read_b128 v[222:225], v141 offset:55392
	ds_read_b128 v[226:229], v141 offset:60000
	ds_read_b128 v[230:233], v140 offset:41568
	s_waitcnt lgkmcnt(4)
	v_mfma_f32_32x32x16_bf16 v[50:65], v[198:201], v[202:205], v[50:65]
	v_mfma_f32_32x32x16_bf16 v[34:49], v[198:201], v[206:209], v[34:49]
	v_mfma_f32_32x32x16_bf16 v[18:33], v[214:217], v[202:205], v[18:33]
	v_mfma_f32_32x32x16_bf16 v[2:17], v[214:217], v[206:209], v[2:17]
	ds_write_b128 v188, v[114:117] offset:18432
	ds_write_b128 v188, v[118:121] offset:23040
	ds_write_b128 v188, v[122:125] offset:27648
	ds_write_b128 v188, v[126:129] offset:32256
	s_waitcnt lgkmcnt(0)
	v_mfma_f32_32x32x16_bf16 v[50:65], v[218:221], v[222:225], v[50:65]
	v_mfma_f32_32x32x16_bf16 v[34:49], v[218:221], v[226:229], v[34:49]
	v_mfma_f32_32x32x16_bf16 v[18:33], v[230:233], v[222:225], v[18:33]
	v_mfma_f32_32x32x16_bf16 v[2:17], v[230:233], v[226:229], v[2:17]
	s_setprio 0
	s_waitcnt lgkmcnt(0)
	s_barrier
	s_setprio 1
	ds_read_b128 v[198:201], v140
	ds_read_b128 v[202:205], v141 offset:18432
	ds_read_b128 v[206:209], v141 offset:23040
	ds_read_b128 v[214:217], v140 offset:4608
	ds_read_b128 v[218:221], v140 offset:32
	ds_read_b128 v[222:225], v141 offset:18464
	ds_read_b128 v[226:229], v141 offset:23072
	ds_read_b128 v[230:233], v140 offset:4640
	s_waitcnt lgkmcnt(4)
	v_mfma_f32_32x32x16_bf16 v[50:65], v[198:201], v[202:205], v[50:65]
	v_mfma_f32_32x32x16_bf16 v[34:49], v[198:201], v[206:209], v[34:49]
	v_mfma_f32_32x32x16_bf16 v[18:33], v[214:217], v[202:205], v[18:33]
	v_mfma_f32_32x32x16_bf16 v[2:17], v[214:217], v[206:209], v[2:17]
	global_load_dwordx4 v[98:101], v[160:161], off offset:512
	global_load_dwordx4 v[102:105], v[162:163], off offset:512
	global_load_dwordx4 v[106:109], v[164:165], off offset:512
	global_load_dwordx4 v[110:113], v[166:167], off offset:512
	global_load_dwordx4 v[114:117], v[158:159], off offset:512
	global_load_dwordx4 v[118:121], v[168:169], off offset:512
	global_load_dwordx4 v[122:125], v[170:171], off offset:512
	global_load_dwordx4 v[126:129], v[172:173], off offset:512
	ds_read_b128 v[198:201], v140 offset:64
	ds_read_b128 v[202:205], v141 offset:18496
	ds_read_b128 v[206:209], v141 offset:23104
	ds_read_b128 v[214:217], v140 offset:4672
	s_waitcnt lgkmcnt(4)
	v_mfma_f32_32x32x16_bf16 v[50:65], v[218:221], v[222:225], v[50:65]
	v_mfma_f32_32x32x16_bf16 v[34:49], v[218:221], v[226:229], v[34:49]
	v_mfma_f32_32x32x16_bf16 v[18:33], v[230:233], v[222:225], v[18:33]
	v_mfma_f32_32x32x16_bf16 v[2:17], v[230:233], v[226:229], v[2:17]
	s_waitcnt vmcnt(8)
	ds_write_b128 v188, v[66:69] offset:36864
	ds_write_b128 v188, v[70:73] offset:41472
	ds_write_b128 v188, v[74:77] offset:46080
	ds_write_b128 v188, v[78:81] offset:50688
	ds_read_b128 v[218:221], v140 offset:96
	ds_read_b128 v[222:225], v141 offset:18528
	ds_read_b128 v[226:229], v141 offset:23136
	ds_read_b128 v[230:233], v140 offset:4704
	s_waitcnt lgkmcnt(4)
	v_mfma_f32_32x32x16_bf16 v[50:65], v[198:201], v[202:205], v[50:65]
	v_mfma_f32_32x32x16_bf16 v[34:49], v[198:201], v[206:209], v[34:49]
	v_mfma_f32_32x32x16_bf16 v[18:33], v[214:217], v[202:205], v[18:33]
	v_mfma_f32_32x32x16_bf16 v[2:17], v[214:217], v[206:209], v[2:17]
	ds_write_b128 v188, v[82:85] offset:55296
	ds_write_b128 v188, v[86:89] offset:59904
	ds_write_b128 v188, v[90:93] offset:64512
	ds_write_b128 v189, v[94:97] offset:13824
	s_waitcnt lgkmcnt(0)
	v_mfma_f32_32x32x16_bf16 v[50:65], v[218:221], v[222:225], v[50:65]
	v_mfma_f32_32x32x16_bf16 v[34:49], v[218:221], v[226:229], v[34:49]
	v_mfma_f32_32x32x16_bf16 v[18:33], v[230:233], v[222:225], v[18:33]
	v_mfma_f32_32x32x16_bf16 v[2:17], v[230:233], v[226:229], v[2:17]
	s_setprio 0
	s_waitcnt lgkmcnt(0)
	s_barrier
; __device__ __forceinline__ void gemm_kstep(const u16* sb, int wn, int wt, int r, int h, f32x16 (&acc)[2][2]) {
;   const u16* bw = sb + (wn * 64 + r) * LDT + h * 8;
;   const u16* bx = sb + TILE_U16 + (wt * 64 + r) * LDT + h * 8;
;   __builtin_amdgcn_s_setprio(1);
; #pragma unroll
;   for (int ks = 0; ks < 4; ++ks) {
;     bf16x8 a0 = *(const bf16x8*)(bw + ks * 16);
;     bf16x8 a1 = *(const bf16x8*)(bw + 32 * LDT + ks * 16);
;     bf16x8 b0 = *(const bf16x8*)(bx + ks * 16);
;     bf16x8 b1 = *(const bf16x8*)(bx + 32 * LDT + ks * 16);
;     acc[0][0] = mfma32(a0, b0, acc[0][0]);
;     acc[0][1] = mfma32(a0, b1, acc[0][1]);
;     acc[1][0] = mfma32(a1, b0, acc[1][0]);
;     acc[1][1] = mfma32(a1, b1, acc[1][1]);
;   }
;   __builtin_amdgcn_s_setprio(0);
; }
; __device__ void gemm_phase(const u16* __restrict__ Wb, int ldw, const u16* __restrict__ Xb, int ldx, int K,
;                            u16* __restrict__ outb, int ldo, int ntn, int ntiles, u16* lds) {
;     ...
;     for (int kt = 0; kt < nk; kt += 2) {
;       if (kt + 2 < nk) gs_load(B, gw, ldw, gx, ldx, (kt + 2) * 64);
;       else if (has_next) gs_load(B, gwn, ldw, gxn, ldx, 0);
;       gemm_kstep(lds, wn, wt, r, h, acc);
;       gs_store(A, lds + 2 * TILE_U16, lo);
;       __syncthreads();
;       if (kt + 3 < nk) gs_load(A, gw, ldw, gx, ldx, (kt + 3) * 64);
;       else if (has_next) gs_load(A, gwn, ldw, gxn, ldx, 64);
;       gemm_kstep(lds + 2 * TILE_U16, wn, wt, r, h, acc);
;       if (kt + 2 < nk) gs_store(B, lds, lo);
;       __syncthreads();
;     }
	s_setprio 1
	ds_read_b128 v[198:201], v140 offset:36864
	ds_read_b128 v[202:205], v141 offset:55296
	ds_read_b128 v[206:209], v141 offset:59904
	ds_read_b128 v[214:217], v140 offset:41472
	ds_read_b128 v[218:221], v140 offset:36896
	ds_read_b128 v[222:225], v141 offset:55328
	ds_read_b128 v[226:229], v141 offset:59936
	ds_read_b128 v[230:233], v140 offset:41504
	s_waitcnt lgkmcnt(4)
	v_mfma_f32_32x32x16_bf16 v[50:65], v[198:201], v[202:205], v[50:65]
	v_mfma_f32_32x32x16_bf16 v[34:49], v[198:201], v[206:209], v[34:49]
	v_mfma_f32_32x32x16_bf16 v[18:33], v[214:217], v[202:205], v[18:33]
	v_mfma_f32_32x32x16_bf16 v[2:17], v[214:217], v[206:209], v[2:17]
	global_load_dwordx4 v[66:69], v[160:161], off offset:640
	global_load_dwordx4 v[70:73], v[162:163], off offset:640
	global_load_dwordx4 v[74:77], v[164:165], off offset:640
	global_load_dwordx4 v[78:81], v[166:167], off offset:640
	global_load_dwordx4 v[82:85], v[158:159], off offset:640
	global_load_dwordx4 v[86:89], v[168:169], off offset:640
	global_load_dwordx4 v[90:93], v[170:171], off offset:640
	global_load_dwordx4 v[94:97], v[172:173], off offset:640
	ds_read_b128 v[198:201], v140 offset:36928
	ds_read_b128 v[202:205], v141 offset:55360
	ds_read_b128 v[206:209], v141 offset:59968
	ds_read_b128 v[214:217], v140 offset:41536
	s_waitcnt lgkmcnt(4)
	v_mfma_f32_32x32x16_bf16 v[50:65], v[218:221], v[222:225], v[50:65]
	v_mfma_f32_32x32x16_bf16 v[34:49], v[218:221], v[226:229], v[34:49]
	v_mfma_f32_32x32x16_bf16 v[18:33], v[230:233], v[222:225], v[18:33]
	v_mfma_f32_32x32x16_bf16 v[2:17], v[230:233], v[226:229], v[2:17]
	s_waitcnt vmcnt(8)
	ds_write_b128 v188, v[98:101]
	ds_write_b128 v188, v[102:105] offset:4608
	ds_write_b128 v188, v[106:109] offset:9216
	ds_write_b128 v188, v[110:113] offset:13824
	ds_read_b128 v[218:221], v140 offset:36960
	ds_read_b128 v[222:225], v141 offset:55392
	ds_read_b128 v[226:229], v141 offset:60000
	ds_read_b128 v[230:233], v140 offset:41568
	s_waitcnt lgkmcnt(4)
	v_mfma_f32_32x32x16_bf16 v[50:65], v[198:201], v[202:205], v[50:65]
	v_mfma_f32_32x32x16_bf16 v[34:49], v[198:201], v[206:209], v[34:49]
	v_mfma_f32_32x32x16_bf16 v[18:33], v[214:217], v[202:205], v[18:33]
	v_mfma_f32_32x32x16_bf16 v[2:17], v[214:217], v[206:209], v[2:17]
	ds_write_b128 v188, v[114:117] offset:18432
	ds_write_b128 v188, v[118:121] offset:23040
	ds_write_b128 v188, v[122:125] offset:27648
	ds_write_b128 v188, v[126:129] offset:32256
	s_waitcnt lgkmcnt(0)
	v_mfma_f32_32x32x16_bf16 v[50:65], v[218:221], v[222:225], v[50:65]
	v_mfma_f32_32x32x16_bf16 v[34:49], v[218:221], v[226:229], v[34:49]
	v_mfma_f32_32x32x16_bf16 v[18:33], v[230:233], v[222:225], v[18:33]
	v_mfma_f32_32x32x16_bf16 v[2:17], v[230:233], v[226:229], v[2:17]
	s_setprio 0
	s_waitcnt lgkmcnt(0)
	s_barrier
	s_setprio 1
	ds_read_b128 v[198:201], v140
	ds_read_b128 v[202:205], v141 offset:18432
	ds_read_b128 v[206:209], v141 offset:23040
	ds_read_b128 v[214:217], v140 offset:4608
	ds_read_b128 v[218:221], v140 offset:32
	ds_read_b128 v[222:225], v141 offset:18464
	ds_read_b128 v[226:229], v141 offset:23072
	ds_read_b128 v[230:233], v140 offset:4640
	s_waitcnt lgkmcnt(4)
	v_mfma_f32_32x32x16_bf16 v[50:65], v[198:201], v[202:205], v[50:65]
	v_mfma_f32_32x32x16_bf16 v[34:49], v[198:201], v[206:209], v[34:49]
	v_mfma_f32_32x32x16_bf16 v[18:33], v[214:217], v[202:205], v[18:33]
	v_mfma_f32_32x32x16_bf16 v[2:17], v[214:217], v[206:209], v[2:17]
	global_load_dwordx4 v[98:101], v[160:161], off offset:768
	global_load_dwordx4 v[102:105], v[162:163], off offset:768
	global_load_dwordx4 v[106:109], v[164:165], off offset:768
	global_load_dwordx4 v[110:113], v[166:167], off offset:768
	global_load_dwordx4 v[114:117], v[158:159], off offset:768
	global_load_dwordx4 v[118:121], v[168:169], off offset:768
	global_load_dwordx4 v[122:125], v[170:171], off offset:768
	global_load_dwordx4 v[126:129], v[172:173], off offset:768
	ds_read_b128 v[198:201], v140 offset:64
	ds_read_b128 v[202:205], v141 offset:18496
	ds_read_b128 v[206:209], v141 offset:23104
	ds_read_b128 v[214:217], v140 offset:4672
	s_waitcnt lgkmcnt(4)
	v_mfma_f32_32x32x16_bf16 v[50:65], v[218:221], v[222:225], v[50:65]
	v_mfma_f32_32x32x16_bf16 v[34:49], v[218:221], v[226:229], v[34:49]
	v_mfma_f32_32x32x16_bf16 v[18:33], v[230:233], v[222:225], v[18:33]
	v_mfma_f32_32x32x16_bf16 v[2:17], v[230:233], v[226:229], v[2:17]
	s_waitcnt vmcnt(8)
	ds_write_b128 v188, v[66:69] offset:36864
	ds_write_b128 v188, v[70:73] offset:41472
	ds_write_b128 v188, v[74:77] offset:46080
	ds_write_b128 v188, v[78:81] offset:50688
	ds_read_b128 v[218:221], v140 offset:96
	ds_read_b128 v[222:225], v141 offset:18528
	ds_read_b128 v[226:229], v141 offset:23136
	ds_read_b128 v[230:233], v140 offset:4704
	s_waitcnt lgkmcnt(4)
	v_mfma_f32_32x32x16_bf16 v[50:65], v[198:201], v[202:205], v[50:65]
	v_mfma_f32_32x32x16_bf16 v[34:49], v[198:201], v[206:209], v[34:49]
	v_mfma_f32_32x32x16_bf16 v[18:33], v[214:217], v[202:205], v[18:33]
	v_mfma_f32_32x32x16_bf16 v[2:17], v[214:217], v[206:209], v[2:17]
	ds_write_b128 v188, v[82:85] offset:55296
	ds_write_b128 v188, v[86:89] offset:59904
	ds_write_b128 v188, v[90:93] offset:64512
	ds_write_b128 v189, v[94:97] offset:13824
	s_waitcnt lgkmcnt(0)
	v_mfma_f32_32x32x16_bf16 v[50:65], v[218:221], v[222:225], v[50:65]
	v_mfma_f32_32x32x16_bf16 v[34:49], v[218:221], v[226:229], v[34:49]
	v_mfma_f32_32x32x16_bf16 v[18:33], v[230:233], v[222:225], v[18:33]
	v_mfma_f32_32x32x16_bf16 v[2:17], v[230:233], v[226:229], v[2:17]
	s_setprio 0
	s_waitcnt lgkmcnt(0)
	s_barrier
; __device__ __forceinline__ void gemm_kstep(const u16* sb, int wn, int wt, int r, int h, f32x16 (&acc)[2][2]) {
;   const u16* bw = sb + (wn * 64 + r) * LDT + h * 8;
;   const u16* bx = sb + TILE_U16 + (wt * 64 + r) * LDT + h * 8;
;   __builtin_amdgcn_s_setprio(1);
; #pragma unroll
;   for (int ks = 0; ks < 4; ++ks) {
;     bf16x8 a0 = *(const bf16x8*)(bw + ks * 16);
;     bf16x8 a1 = *(const bf16x8*)(bw + 32 * LDT + ks * 16);
;     bf16x8 b0 = *(const bf16x8*)(bx + ks * 16);
;     bf16x8 b1 = *(const bf16x8*)(bx + 32 * LDT + ks * 16);
;     acc[0][0] = mfma32(a0, b0, acc[0][0]);
;     acc[0][1] = mfma32(a0, b1, acc[0][1]);
;     acc[1][0] = mfma32(a1, b0, acc[1][0]);
;     acc[1][1] = mfma32(a1, b1, acc[1][1]);
;   }
;   __builtin_amdgcn_s_setprio(0);
; }
; __device__ void gemm_phase(const u16* __restrict__ Wb, int ldw, const u16* __restrict__ Xb, int ldx, int K,
;                            u16* __restrict__ outb, int ldo, int ntn, int ntiles, u16* lds) {
;     ...
;     for (int kt = 0; kt < nk; kt += 2) {
;       if (kt + 2 < nk) gs_load(B, gw, ldw, gx, ldx, (kt + 2) * 64);
;       else if (has_next) gs_load(B, gwn, ldw, gxn, ldx, 0);
;       gemm_kstep(lds, wn, wt, r, h, acc);
;       gs_store(A, lds + 2 * TILE_U16, lo);
;       __syncthreads();
;       if (kt + 3 < nk) gs_load(A, gw, ldw, gx, ldx, (kt + 3) * 64);
;       else if (has_next) gs_load(A, gwn, ldw, gxn, ldx, 64);
;       gemm_kstep(lds + 2 * TILE_U16, wn, wt, r, h, acc);
;       if (kt + 2 < nk) gs_store(B, lds, lo);
;       __syncthreads();
;     }
	s_setprio 1
	ds_read_b128 v[198:201], v140 offset:36864
	ds_read_b128 v[202:205], v141 offset:55296
	ds_read_b128 v[206:209], v141 offset:59904
	ds_read_b128 v[214:217], v140 offset:41472
	ds_read_b128 v[218:221], v140 offset:36896
	ds_read_b128 v[222:225], v141 offset:55328
	ds_read_b128 v[226:229], v141 offset:59936
	ds_read_b128 v[230:233], v140 offset:41504
	s_waitcnt lgkmcnt(4)
	v_mfma_f32_32x32x16_bf16 v[50:65], v[198:201], v[202:205], v[50:65]
	v_mfma_f32_32x32x16_bf16 v[34:49], v[198:201], v[206:209], v[34:49]
	v_mfma_f32_32x32x16_bf16 v[18:33], v[214:217], v[202:205], v[18:33]
	v_mfma_f32_32x32x16_bf16 v[2:17], v[214:217], v[206:209], v[2:17]
	global_load_dwordx4 v[66:69], v[160:161], off offset:896
	global_load_dwordx4 v[70:73], v[162:163], off offset:896
	global_load_dwordx4 v[74:77], v[164:165], off offset:896
	global_load_dwordx4 v[78:81], v[166:167], off offset:896
	global_load_dwordx4 v[82:85], v[158:159], off offset:896
	global_load_dwordx4 v[86:89], v[168:169], off offset:896
	global_load_dwordx4 v[90:93], v[170:171], off offset:896
	global_load_dwordx4 v[94:97], v[172:173], off offset:896
	ds_read_b128 v[198:201], v140 offset:36928
	ds_read_b128 v[202:205], v141 offset:55360
	ds_read_b128 v[206:209], v141 offset:59968
	ds_read_b128 v[214:217], v140 offset:41536
	s_waitcnt lgkmcnt(4)
	v_mfma_f32_32x32x16_bf16 v[50:65], v[218:221], v[222:225], v[50:65]
	v_mfma_f32_32x32x16_bf16 v[34:49], v[218:221], v[226:229], v[34:49]
	v_mfma_f32_32x32x16_bf16 v[18:33], v[230:233], v[222:225], v[18:33]
	v_mfma_f32_32x32x16_bf16 v[2:17], v[230:233], v[226:229], v[2:17]
	s_waitcnt vmcnt(8)
	ds_write_b128 v188, v[98:101]
	ds_write_b128 v188, v[102:105] offset:4608
	ds_write_b128 v188, v[106:109] offset:9216
	ds_write_b128 v188, v[110:113] offset:13824
	ds_read_b128 v[218:221], v140 offset:36960
	ds_read_b128 v[222:225], v141 offset:55392
	ds_read_b128 v[226:229], v141 offset:60000
	ds_read_b128 v[230:233], v140 offset:41568
	s_waitcnt lgkmcnt(4)
	v_mfma_f32_32x32x16_bf16 v[50:65], v[198:201], v[202:205], v[50:65]
	v_mfma_f32_32x32x16_bf16 v[34:49], v[198:201], v[206:209], v[34:49]
	v_mfma_f32_32x32x16_bf16 v[18:33], v[214:217], v[202:205], v[18:33]
	v_mfma_f32_32x32x16_bf16 v[2:17], v[214:217], v[206:209], v[2:17]
	ds_write_b128 v188, v[114:117] offset:18432
	ds_write_b128 v188, v[118:121] offset:23040
	ds_write_b128 v188, v[122:125] offset:27648
	ds_write_b128 v188, v[126:129] offset:32256
	s_waitcnt lgkmcnt(0)
	v_mfma_f32_32x32x16_bf16 v[50:65], v[218:221], v[222:225], v[50:65]
	v_mfma_f32_32x32x16_bf16 v[34:49], v[218:221], v[226:229], v[34:49]
	v_mfma_f32_32x32x16_bf16 v[18:33], v[230:233], v[222:225], v[18:33]
	v_mfma_f32_32x32x16_bf16 v[2:17], v[230:233], v[226:229], v[2:17]
	s_setprio 0
	s_waitcnt lgkmcnt(0)
	s_barrier
	s_setprio 1
	ds_read_b128 v[198:201], v140
	ds_read_b128 v[202:205], v141 offset:18432
	ds_read_b128 v[206:209], v141 offset:23040
	ds_read_b128 v[214:217], v140 offset:4608
	ds_read_b128 v[218:221], v140 offset:32
	ds_read_b128 v[222:225], v141 offset:18464
	ds_read_b128 v[226:229], v141 offset:23072
	ds_read_b128 v[230:233], v140 offset:4640
	s_waitcnt lgkmcnt(4)
	v_mfma_f32_32x32x16_bf16 v[50:65], v[198:201], v[202:205], v[50:65]
	v_mfma_f32_32x32x16_bf16 v[34:49], v[198:201], v[206:209], v[34:49]
	v_mfma_f32_32x32x16_bf16 v[18:33], v[214:217], v[202:205], v[18:33]
	v_mfma_f32_32x32x16_bf16 v[2:17], v[214:217], v[206:209], v[2:17]
	global_load_dwordx4 v[98:101], v[160:161], off offset:1024
	global_load_dwordx4 v[102:105], v[162:163], off offset:1024
	global_load_dwordx4 v[106:109], v[164:165], off offset:1024
	global_load_dwordx4 v[110:113], v[166:167], off offset:1024
	global_load_dwordx4 v[114:117], v[158:159], off offset:1024
	global_load_dwordx4 v[118:121], v[168:169], off offset:1024
	global_load_dwordx4 v[122:125], v[170:171], off offset:1024
	global_load_dwordx4 v[126:129], v[172:173], off offset:1024
	ds_read_b128 v[198:201], v140 offset:64
	ds_read_b128 v[202:205], v141 offset:18496
	ds_read_b128 v[206:209], v141 offset:23104
	ds_read_b128 v[214:217], v140 offset:4672
	s_waitcnt lgkmcnt(4)
	v_mfma_f32_32x32x16_bf16 v[50:65], v[218:221], v[222:225], v[50:65]
	v_mfma_f32_32x32x16_bf16 v[34:49], v[218:221], v[226:229], v[34:49]
	v_mfma_f32_32x32x16_bf16 v[18:33], v[230:233], v[222:225], v[18:33]
	v_mfma_f32_32x32x16_bf16 v[2:17], v[230:233], v[226:229], v[2:17]
	s_waitcnt vmcnt(8)
	ds_write_b128 v188, v[66:69] offset:36864
	ds_write_b128 v188, v[70:73] offset:41472
	ds_write_b128 v188, v[74:77] offset:46080
	ds_write_b128 v188, v[78:81] offset:50688
	ds_read_b128 v[218:221], v140 offset:96
	ds_read_b128 v[222:225], v141 offset:18528
	ds_read_b128 v[226:229], v141 offset:23136
	ds_read_b128 v[230:233], v140 offset:4704
	s_waitcnt lgkmcnt(4)
	v_mfma_f32_32x32x16_bf16 v[50:65], v[198:201], v[202:205], v[50:65]
	v_mfma_f32_32x32x16_bf16 v[34:49], v[198:201], v[206:209], v[34:49]
	v_mfma_f32_32x32x16_bf16 v[18:33], v[214:217], v[202:205], v[18:33]
	v_mfma_f32_32x32x16_bf16 v[2:17], v[214:217], v[206:209], v[2:17]
	ds_write_b128 v188, v[82:85] offset:55296
	ds_write_b128 v188, v[86:89] offset:59904
	ds_write_b128 v188, v[90:93] offset:64512
	ds_write_b128 v189, v[94:97] offset:13824
	s_waitcnt lgkmcnt(0)
	v_mfma_f32_32x32x16_bf16 v[50:65], v[218:221], v[222:225], v[50:65]
	v_mfma_f32_32x32x16_bf16 v[34:49], v[218:221], v[226:229], v[34:49]
	v_mfma_f32_32x32x16_bf16 v[18:33], v[230:233], v[222:225], v[18:33]
	v_mfma_f32_32x32x16_bf16 v[2:17], v[230:233], v[226:229], v[2:17]
	s_setprio 0
	s_waitcnt lgkmcnt(0)
	s_barrier
; __device__ __forceinline__ void gemm_kstep(const u16* sb, int wn, int wt, int r, int h, f32x16 (&acc)[2][2]) {
;   const u16* bw = sb + (wn * 64 + r) * LDT + h * 8;
;   const u16* bx = sb + TILE_U16 + (wt * 64 + r) * LDT + h * 8;
;   __builtin_amdgcn_s_setprio(1);
; #pragma unroll
;   for (int ks = 0; ks < 4; ++ks) {
;     bf16x8 a0 = *(const bf16x8*)(bw + ks * 16);
;     bf16x8 a1 = *(const bf16x8*)(bw + 32 * LDT + ks * 16);
;     bf16x8 b0 = *(const bf16x8*)(bx + ks * 16);
;     bf16x8 b1 = *(const bf16x8*)(bx + 32 * LDT + ks * 16);
;     acc[0][0] = mfma32(a0, b0, acc[0][0]);
;     acc[0][1] = mfma32(a0, b1, acc[0][1]);
;     acc[1][0] = mfma32(a1, b0, acc[1][0]);
;     acc[1][1] = mfma32(a1, b1, acc[1][1]);
;   }
;   __builtin_amdgcn_s_setprio(0);
; }
; __device__ void gemm_phase(const u16* __restrict__ Wb, int ldw, const u16* __restrict__ Xb, int ldx, int K,
;                            u16* __restrict__ outb, int ldo, int ntn, int ntiles, u16* lds) {
;     ...
;     for (int kt = 0; kt < nk; kt += 2) {
;       if (kt + 2 < nk) gs_load(B, gw, ldw, gx, ldx, (kt + 2) * 64);
;       else if (has_next) gs_load(B, gwn, ldw, gxn, ldx, 0);
;       gemm_kstep(lds, wn, wt, r, h, acc);
;       gs_store(A, lds + 2 * TILE_U16, lo);
;       __syncthreads();
;       if (kt + 3 < nk) gs_load(A, gw, ldw, gx, ldx, (kt + 3) * 64);
;       else if (has_next) gs_load(A, gwn, ldw, gxn, ldx, 64);
;       gemm_kstep(lds + 2 * TILE_U16, wn, wt, r, h, acc);
;       if (kt + 2 < nk) gs_store(B, lds, lo);
;       __syncthreads();
;     }
	s_setprio 1
	ds_read_b128 v[198:201], v140 offset:36864
	ds_read_b128 v[202:205], v141 offset:55296
	ds_read_b128 v[206:209], v141 offset:59904
	ds_read_b128 v[214:217], v140 offset:41472
	ds_read_b128 v[218:221], v140 offset:36896
	ds_read_b128 v[222:225], v141 offset:55328
	ds_read_b128 v[226:229], v141 offset:59936
	ds_read_b128 v[230:233], v140 offset:41504
	s_waitcnt lgkmcnt(4)
	v_mfma_f32_32x32x16_bf16 v[50:65], v[198:201], v[202:205], v[50:65]
	v_mfma_f32_32x32x16_bf16 v[34:49], v[198:201], v[206:209], v[34:49]
	v_mfma_f32_32x32x16_bf16 v[18:33], v[214:217], v[202:205], v[18:33]
	v_mfma_f32_32x32x16_bf16 v[2:17], v[214:217], v[206:209], v[2:17]
	global_load_dwordx4 v[66:69], v[160:161], off offset:1152
	global_load_dwordx4 v[70:73], v[162:163], off offset:1152
	global_load_dwordx4 v[74:77], v[164:165], off offset:1152
	global_load_dwordx4 v[78:81], v[166:167], off offset:1152
	global_load_dwordx4 v[82:85], v[158:159], off offset:1152
	global_load_dwordx4 v[86:89], v[168:169], off offset:1152
	global_load_dwordx4 v[90:93], v[170:171], off offset:1152
	global_load_dwordx4 v[94:97], v[172:173], off offset:1152
	ds_read_b128 v[198:201], v140 offset:36928
	ds_read_b128 v[202:205], v141 offset:55360
	ds_read_b128 v[206:209], v141 offset:59968
	ds_read_b128 v[214:217], v140 offset:41536
	s_waitcnt lgkmcnt(4)
	v_mfma_f32_32x32x16_bf16 v[50:65], v[218:221], v[222:225], v[50:65]
	v_mfma_f32_32x32x16_bf16 v[34:49], v[218:221], v[226:229], v[34:49]
	v_mfma_f32_32x32x16_bf16 v[18:33], v[230:233], v[222:225], v[18:33]
	v_mfma_f32_32x32x16_bf16 v[2:17], v[230:233], v[226:229], v[2:17]
	s_waitcnt vmcnt(8)
	ds_write_b128 v188, v[98:101]
	ds_write_b128 v188, v[102:105] offset:4608
	ds_write_b128 v188, v[106:109] offset:9216
	ds_write_b128 v188, v[110:113] offset:13824
	ds_read_b128 v[218:221], v140 offset:36960
	ds_read_b128 v[222:225], v141 offset:55392
	ds_read_b128 v[226:229], v141 offset:60000
	ds_read_b128 v[230:233], v140 offset:41568
	s_waitcnt lgkmcnt(4)
	v_mfma_f32_32x32x16_bf16 v[50:65], v[198:201], v[202:205], v[50:65]
	v_mfma_f32_32x32x16_bf16 v[34:49], v[198:201], v[206:209], v[34:49]
	v_mfma_f32_32x32x16_bf16 v[18:33], v[214:217], v[202:205], v[18:33]
	v_mfma_f32_32x32x16_bf16 v[2:17], v[214:217], v[206:209], v[2:17]
	ds_write_b128 v188, v[114:117] offset:18432
	ds_write_b128 v188, v[118:121] offset:23040
	ds_write_b128 v188, v[122:125] offset:27648
	ds_write_b128 v188, v[126:129] offset:32256
	s_waitcnt lgkmcnt(0)
	v_mfma_f32_32x32x16_bf16 v[50:65], v[218:221], v[222:225], v[50:65]
	v_mfma_f32_32x32x16_bf16 v[34:49], v[218:221], v[226:229], v[34:49]
	v_mfma_f32_32x32x16_bf16 v[18:33], v[230:233], v[222:225], v[18:33]
	v_mfma_f32_32x32x16_bf16 v[2:17], v[230:233], v[226:229], v[2:17]
	s_setprio 0
	s_waitcnt lgkmcnt(0)
	s_barrier
	s_setprio 1
	ds_read_b128 v[198:201], v140
	ds_read_b128 v[202:205], v141 offset:18432
	ds_read_b128 v[206:209], v141 offset:23040
	ds_read_b128 v[214:217], v140 offset:4608
	ds_read_b128 v[218:221], v140 offset:32
	ds_read_b128 v[222:225], v141 offset:18464
	ds_read_b128 v[226:229], v141 offset:23072
	ds_read_b128 v[230:233], v140 offset:4640
	s_waitcnt lgkmcnt(4)
	v_mfma_f32_32x32x16_bf16 v[50:65], v[198:201], v[202:205], v[50:65]
	v_mfma_f32_32x32x16_bf16 v[34:49], v[198:201], v[206:209], v[34:49]
	v_mfma_f32_32x32x16_bf16 v[18:33], v[214:217], v[202:205], v[18:33]
	v_mfma_f32_32x32x16_bf16 v[2:17], v[214:217], v[206:209], v[2:17]
	global_load_dwordx4 v[98:101], v[160:161], off offset:1280
	global_load_dwordx4 v[102:105], v[162:163], off offset:1280
	global_load_dwordx4 v[106:109], v[164:165], off offset:1280
	global_load_dwordx4 v[110:113], v[166:167], off offset:1280
	global_load_dwordx4 v[114:117], v[158:159], off offset:1280
	global_load_dwordx4 v[118:121], v[168:169], off offset:1280
	global_load_dwordx4 v[122:125], v[170:171], off offset:1280
	global_load_dwordx4 v[126:129], v[172:173], off offset:1280
	ds_read_b128 v[198:201], v140 offset:64
	ds_read_b128 v[202:205], v141 offset:18496
	ds_read_b128 v[206:209], v141 offset:23104
	ds_read_b128 v[214:217], v140 offset:4672
	s_waitcnt lgkmcnt(4)
	v_mfma_f32_32x32x16_bf16 v[50:65], v[218:221], v[222:225], v[50:65]
	v_mfma_f32_32x32x16_bf16 v[34:49], v[218:221], v[226:229], v[34:49]
	v_mfma_f32_32x32x16_bf16 v[18:33], v[230:233], v[222:225], v[18:33]
	v_mfma_f32_32x32x16_bf16 v[2:17], v[230:233], v[226:229], v[2:17]
	s_waitcnt vmcnt(8)
	ds_write_b128 v188, v[66:69] offset:36864
	ds_write_b128 v188, v[70:73] offset:41472
	ds_write_b128 v188, v[74:77] offset:46080
	ds_write_b128 v188, v[78:81] offset:50688
	ds_read_b128 v[218:221], v140 offset:96
	ds_read_b128 v[222:225], v141 offset:18528
	ds_read_b128 v[226:229], v141 offset:23136
	ds_read_b128 v[230:233], v140 offset:4704
	s_waitcnt lgkmcnt(4)
	v_mfma_f32_32x32x16_bf16 v[50:65], v[198:201], v[202:205], v[50:65]
	v_mfma_f32_32x32x16_bf16 v[34:49], v[198:201], v[206:209], v[34:49]
	v_mfma_f32_32x32x16_bf16 v[18:33], v[214:217], v[202:205], v[18:33]
	v_mfma_f32_32x32x16_bf16 v[2:17], v[214:217], v[206:209], v[2:17]
	ds_write_b128 v188, v[82:85] offset:55296
	ds_write_b128 v188, v[86:89] offset:59904
	ds_write_b128 v188, v[90:93] offset:64512
	ds_write_b128 v189, v[94:97] offset:13824
	s_waitcnt lgkmcnt(0)
	v_mfma_f32_32x32x16_bf16 v[50:65], v[218:221], v[222:225], v[50:65]
	v_mfma_f32_32x32x16_bf16 v[34:49], v[218:221], v[226:229], v[34:49]
	v_mfma_f32_32x32x16_bf16 v[18:33], v[230:233], v[222:225], v[18:33]
	v_mfma_f32_32x32x16_bf16 v[2:17], v[230:233], v[226:229], v[2:17]
	s_setprio 0
	s_waitcnt lgkmcnt(0)
	s_barrier
; __device__ __forceinline__ void gemm_kstep(const u16* sb, int wn, int wt, int r, int h, f32x16 (&acc)[2][2]) {
;   const u16* bw = sb + (wn * 64 + r) * LDT + h * 8;
;   const u16* bx = sb + TILE_U16 + (wt * 64 + r) * LDT + h * 8;
;   __builtin_amdgcn_s_setprio(1);
; #pragma unroll
;   for (int ks = 0; ks < 4; ++ks) {
;     bf16x8 a0 = *(const bf16x8*)(bw + ks * 16);
;     bf16x8 a1 = *(const bf16x8*)(bw + 32 * LDT + ks * 16);
;     bf16x8 b0 = *(const bf16x8*)(bx + ks * 16);
;     bf16x8 b1 = *(const bf16x8*)(bx + 32 * LDT + ks * 16);
;     acc[0][0] = mfma32(a0, b0, acc[0][0]);
;     acc[0][1] = mfma32(a0, b1, acc[0][1]);
;     acc[1][0] = mfma32(a1, b0, acc[1][0]);
;     acc[1][1] = mfma32(a1, b1, acc[1][1]);
;   }
;   __builtin_amdgcn_s_setprio(0);
; }
; __device__ void gemm_phase(const u16* __restrict__ Wb, int ldw, const u16* __restrict__ Xb, int ldx, int K,
;                            u16* __restrict__ outb, int ldo, int ntn, int ntiles, u16* lds) {
;     ...
;     for (int kt = 0; kt < nk; kt += 2) {
;       if (kt + 2 < nk) gs_load(B, gw, ldw, gx, ldx, (kt + 2) * 64);
;       else if (has_next) gs_load(B, gwn, ldw, gxn, ldx, 0);
;       gemm_kstep(lds, wn, wt, r, h, acc);
;       gs_store(A, lds + 2 * TILE_U16, lo);
;       __syncthreads();
;       if (kt + 3 < nk) gs_load(A, gw, ldw, gx, ldx, (kt + 3) * 64);
;       else if (has_next) gs_load(A, gwn, ldw, gxn, ldx, 64);
;       gemm_kstep(lds + 2 * TILE_U16, wn, wt, r, h, acc);
;       if (kt + 2 < nk) gs_store(B, lds, lo);
;       __syncthreads();
;     }
	s_setprio 1
	ds_read_b128 v[198:201], v140 offset:36864
	ds_read_b128 v[202:205], v141 offset:55296
	ds_read_b128 v[206:209], v141 offset:59904
	ds_read_b128 v[214:217], v140 offset:41472
	ds_read_b128 v[218:221], v140 offset:36896
	ds_read_b128 v[222:225], v141 offset:55328
	ds_read_b128 v[226:229], v141 offset:59936
	ds_read_b128 v[230:233], v140 offset:41504
	s_waitcnt lgkmcnt(4)
	v_mfma_f32_32x32x16_bf16 v[50:65], v[198:201], v[202:205], v[50:65]
	v_mfma_f32_32x32x16_bf16 v[34:49], v[198:201], v[206:209], v[34:49]
	v_mfma_f32_32x32x16_bf16 v[18:33], v[214:217], v[202:205], v[18:33]
	v_mfma_f32_32x32x16_bf16 v[2:17], v[214:217], v[206:209], v[2:17]
	global_load_dwordx4 v[66:69], v[160:161], off offset:1408
	global_load_dwordx4 v[70:73], v[162:163], off offset:1408
	global_load_dwordx4 v[74:77], v[164:165], off offset:1408
	global_load_dwordx4 v[78:81], v[166:167], off offset:1408
	global_load_dwordx4 v[82:85], v[158:159], off offset:1408
	global_load_dwordx4 v[86:89], v[168:169], off offset:1408
	global_load_dwordx4 v[90:93], v[170:171], off offset:1408
	global_load_dwordx4 v[94:97], v[172:173], off offset:1408
	ds_read_b128 v[198:201], v140 offset:36928
	ds_read_b128 v[202:205], v141 offset:55360
	ds_read_b128 v[206:209], v141 offset:59968
	ds_read_b128 v[214:217], v140 offset:41536
	s_waitcnt lgkmcnt(4)
	v_mfma_f32_32x32x16_bf16 v[50:65], v[218:221], v[222:225], v[50:65]
	v_mfma_f32_32x32x16_bf16 v[34:49], v[218:221], v[226:229], v[34:49]
	v_mfma_f32_32x32x16_bf16 v[18:33], v[230:233], v[222:225], v[18:33]
	v_mfma_f32_32x32x16_bf16 v[2:17], v[230:233], v[226:229], v[2:17]
	s_waitcnt vmcnt(8)
	ds_write_b128 v188, v[98:101]
	ds_write_b128 v188, v[102:105] offset:4608
	ds_write_b128 v188, v[106:109] offset:9216
	ds_write_b128 v188, v[110:113] offset:13824
	ds_read_b128 v[218:221], v140 offset:36960
	ds_read_b128 v[222:225], v141 offset:55392
	ds_read_b128 v[226:229], v141 offset:60000
	ds_read_b128 v[230:233], v140 offset:41568
	s_waitcnt lgkmcnt(4)
	v_mfma_f32_32x32x16_bf16 v[50:65], v[198:201], v[202:205], v[50:65]
	v_mfma_f32_32x32x16_bf16 v[34:49], v[198:201], v[206:209], v[34:49]
	v_mfma_f32_32x32x16_bf16 v[18:33], v[214:217], v[202:205], v[18:33]
	v_mfma_f32_32x32x16_bf16 v[2:17], v[214:217], v[206:209], v[2:17]
	ds_write_b128 v188, v[114:117] offset:18432
	ds_write_b128 v188, v[118:121] offset:23040
	ds_write_b128 v188, v[122:125] offset:27648
	ds_write_b128 v188, v[126:129] offset:32256
	s_waitcnt lgkmcnt(0)
	v_mfma_f32_32x32x16_bf16 v[50:65], v[218:221], v[222:225], v[50:65]
	v_mfma_f32_32x32x16_bf16 v[34:49], v[218:221], v[226:229], v[34:49]
	v_mfma_f32_32x32x16_bf16 v[18:33], v[230:233], v[222:225], v[18:33]
	v_mfma_f32_32x32x16_bf16 v[2:17], v[230:233], v[226:229], v[2:17]
	s_setprio 0
	s_waitcnt lgkmcnt(0)
	s_barrier
	s_setprio 1
	ds_read_b128 v[198:201], v140
	ds_read_b128 v[202:205], v141 offset:18432
	ds_read_b128 v[206:209], v141 offset:23040
	ds_read_b128 v[214:217], v140 offset:4608
	ds_read_b128 v[218:221], v140 offset:32
	ds_read_b128 v[222:225], v141 offset:18464
	ds_read_b128 v[226:229], v141 offset:23072
	ds_read_b128 v[230:233], v140 offset:4640
	s_waitcnt lgkmcnt(4)
	v_mfma_f32_32x32x16_bf16 v[50:65], v[198:201], v[202:205], v[50:65]
	v_mfma_f32_32x32x16_bf16 v[34:49], v[198:201], v[206:209], v[34:49]
	v_mfma_f32_32x32x16_bf16 v[18:33], v[214:217], v[202:205], v[18:33]
	v_mfma_f32_32x32x16_bf16 v[2:17], v[214:217], v[206:209], v[2:17]
	global_load_dwordx4 v[98:101], v[160:161], off offset:1536
	global_load_dwordx4 v[102:105], v[162:163], off offset:1536
	global_load_dwordx4 v[106:109], v[164:165], off offset:1536
	global_load_dwordx4 v[110:113], v[166:167], off offset:1536
	global_load_dwordx4 v[114:117], v[158:159], off offset:1536
	global_load_dwordx4 v[118:121], v[168:169], off offset:1536
	global_load_dwordx4 v[122:125], v[170:171], off offset:1536
	global_load_dwordx4 v[126:129], v[172:173], off offset:1536
	ds_read_b128 v[198:201], v140 offset:64
	ds_read_b128 v[202:205], v141 offset:18496
	ds_read_b128 v[206:209], v141 offset:23104
	ds_read_b128 v[214:217], v140 offset:4672
	s_waitcnt lgkmcnt(4)
	v_mfma_f32_32x32x16_bf16 v[50:65], v[218:221], v[222:225], v[50:65]
	v_mfma_f32_32x32x16_bf16 v[34:49], v[218:221], v[226:229], v[34:49]
	v_mfma_f32_32x32x16_bf16 v[18:33], v[230:233], v[222:225], v[18:33]
	v_mfma_f32_32x32x16_bf16 v[2:17], v[230:233], v[226:229], v[2:17]
	s_waitcnt vmcnt(8)
	ds_write_b128 v188, v[66:69] offset:36864
	ds_write_b128 v188, v[70:73] offset:41472
	ds_write_b128 v188, v[74:77] offset:46080
	ds_write_b128 v188, v[78:81] offset:50688
	ds_read_b128 v[218:221], v140 offset:96
	ds_read_b128 v[222:225], v141 offset:18528
	ds_read_b128 v[226:229], v141 offset:23136
	ds_read_b128 v[230:233], v140 offset:4704
	s_waitcnt lgkmcnt(4)
	v_mfma_f32_32x32x16_bf16 v[50:65], v[198:201], v[202:205], v[50:65]
	v_mfma_f32_32x32x16_bf16 v[34:49], v[198:201], v[206:209], v[34:49]
	v_mfma_f32_32x32x16_bf16 v[18:33], v[214:217], v[202:205], v[18:33]
	v_mfma_f32_32x32x16_bf16 v[2:17], v[214:217], v[206:209], v[2:17]
	ds_write_b128 v188, v[82:85] offset:55296
	ds_write_b128 v188, v[86:89] offset:59904
	ds_write_b128 v188, v[90:93] offset:64512
	ds_write_b128 v189, v[94:97] offset:13824
	s_waitcnt lgkmcnt(0)
	v_mfma_f32_32x32x16_bf16 v[50:65], v[218:221], v[222:225], v[50:65]
	v_mfma_f32_32x32x16_bf16 v[34:49], v[218:221], v[226:229], v[34:49]
	v_mfma_f32_32x32x16_bf16 v[18:33], v[230:233], v[222:225], v[18:33]
	v_mfma_f32_32x32x16_bf16 v[2:17], v[230:233], v[226:229], v[2:17]
	s_setprio 0
	s_waitcnt lgkmcnt(0)
	s_barrier
; __device__ __forceinline__ void gemm_kstep(const u16* sb, int wn, int wt, int r, int h, f32x16 (&acc)[2][2]) {
;   const u16* bw = sb + (wn * 64 + r) * LDT + h * 8;
;   const u16* bx = sb + TILE_U16 + (wt * 64 + r) * LDT + h * 8;
;   __builtin_amdgcn_s_setprio(1);
; #pragma unroll
;   for (int ks = 0; ks < 4; ++ks) {
;     bf16x8 a0 = *(const bf16x8*)(bw + ks * 16);
;     bf16x8 a1 = *(const bf16x8*)(bw + 32 * LDT + ks * 16);
;     bf16x8 b0 = *(const bf16x8*)(bx + ks * 16);
;     bf16x8 b1 = *(const bf16x8*)(bx + 32 * LDT + ks * 16);
;     acc[0][0] = mfma32(a0, b0, acc[0][0]);
;     acc[0][1] = mfma32(a0, b1, acc[0][1]);
;     acc[1][0] = mfma32(a1, b0, acc[1][0]);
;     acc[1][1] = mfma32(a1, b1, acc[1][1]);
;   }
;   __builtin_amdgcn_s_setprio(0);
; }
; __device__ void gemm_phase(const u16* __restrict__ Wb, int ldw, const u16* __restrict__ Xb, int ldx, int K,
;                            u16* __restrict__ outb, int ldo, int ntn, int ntiles, u16* lds) {
;     ...
;     for (int kt = 0; kt < nk; kt += 2) {
;       if (kt + 2 < nk) gs_load(B, gw, ldw, gx, ldx, (kt + 2) * 64);
;       else if (has_next) gs_load(B, gwn, ldw, gxn, ldx, 0);
;       gemm_kstep(lds, wn, wt, r, h, acc);
;       gs_store(A, lds + 2 * TILE_U16, lo);
;       __syncthreads();
;       if (kt + 3 < nk) gs_load(A, gw, ldw, gx, ldx, (kt + 3) * 64);
;       else if (has_next) gs_load(A, gwn, ldw, gxn, ldx, 64);
;       gemm_kstep(lds + 2 * TILE_U16, wn, wt, r, h, acc);
;       if (kt + 2 < nk) gs_store(B, lds, lo);
;       __syncthreads();
;     }
	s_setprio 1
	ds_read_b128 v[198:201], v140 offset:36864
	ds_read_b128 v[202:205], v141 offset:55296
	ds_read_b128 v[206:209], v141 offset:59904
	ds_read_b128 v[214:217], v140 offset:41472
	ds_read_b128 v[218:221], v140 offset:36896
	ds_read_b128 v[222:225], v141 offset:55328
	ds_read_b128 v[226:229], v141 offset:59936
	ds_read_b128 v[230:233], v140 offset:41504
	s_waitcnt lgkmcnt(4)
	v_mfma_f32_32x32x16_bf16 v[50:65], v[198:201], v[202:205], v[50:65]
	v_mfma_f32_32x32x16_bf16 v[34:49], v[198:201], v[206:209], v[34:49]
	v_mfma_f32_32x32x16_bf16 v[18:33], v[214:217], v[202:205], v[18:33]
	v_mfma_f32_32x32x16_bf16 v[2:17], v[214:217], v[206:209], v[2:17]
	global_load_dwordx4 v[66:69], v[160:161], off offset:1664
	global_load_dwordx4 v[70:73], v[162:163], off offset:1664
	global_load_dwordx4 v[74:77], v[164:165], off offset:1664
	global_load_dwordx4 v[78:81], v[166:167], off offset:1664
	global_load_dwordx4 v[82:85], v[158:159], off offset:1664
	global_load_dwordx4 v[86:89], v[168:169], off offset:1664
	global_load_dwordx4 v[90:93], v[170:171], off offset:1664
	global_load_dwordx4 v[94:97], v[172:173], off offset:1664
	ds_read_b128 v[198:201], v140 offset:36928
	ds_read_b128 v[202:205], v141 offset:55360
	ds_read_b128 v[206:209], v141 offset:59968
	ds_read_b128 v[214:217], v140 offset:41536
	s_waitcnt lgkmcnt(4)
	v_mfma_f32_32x32x16_bf16 v[50:65], v[218:221], v[222:225], v[50:65]
	v_mfma_f32_32x32x16_bf16 v[34:49], v[218:221], v[226:229], v[34:49]
	v_mfma_f32_32x32x16_bf16 v[18:33], v[230:233], v[222:225], v[18:33]
	v_mfma_f32_32x32x16_bf16 v[2:17], v[230:233], v[226:229], v[2:17]
	s_waitcnt vmcnt(8)
	ds_write_b128 v188, v[98:101]
	ds_write_b128 v188, v[102:105] offset:4608
	ds_write_b128 v188, v[106:109] offset:9216
	ds_write_b128 v188, v[110:113] offset:13824
	ds_read_b128 v[218:221], v140 offset:36960
	ds_read_b128 v[222:225], v141 offset:55392
	ds_read_b128 v[226:229], v141 offset:60000
	ds_read_b128 v[230:233], v140 offset:41568
	s_waitcnt lgkmcnt(4)
	v_mfma_f32_32x32x16_bf16 v[50:65], v[198:201], v[202:205], v[50:65]
	v_mfma_f32_32x32x16_bf16 v[34:49], v[198:201], v[206:209], v[34:49]
	v_mfma_f32_32x32x16_bf16 v[18:33], v[214:217], v[202:205], v[18:33]
	v_mfma_f32_32x32x16_bf16 v[2:17], v[214:217], v[206:209], v[2:17]
	ds_write_b128 v188, v[114:117] offset:18432
	ds_write_b128 v188, v[118:121] offset:23040
	ds_write_b128 v188, v[122:125] offset:27648
	ds_write_b128 v188, v[126:129] offset:32256
	s_waitcnt lgkmcnt(0)
	v_mfma_f32_32x32x16_bf16 v[50:65], v[218:221], v[222:225], v[50:65]
	v_mfma_f32_32x32x16_bf16 v[34:49], v[218:221], v[226:229], v[34:49]
	v_mfma_f32_32x32x16_bf16 v[18:33], v[230:233], v[222:225], v[18:33]
	v_mfma_f32_32x32x16_bf16 v[2:17], v[230:233], v[226:229], v[2:17]
	s_setprio 0
	s_waitcnt lgkmcnt(0)
	s_barrier
	s_setprio 1
	ds_read_b128 v[198:201], v140
	ds_read_b128 v[202:205], v141 offset:18432
	ds_read_b128 v[206:209], v141 offset:23040
	ds_read_b128 v[214:217], v140 offset:4608
	ds_read_b128 v[218:221], v140 offset:32
	ds_read_b128 v[222:225], v141 offset:18464
	ds_read_b128 v[226:229], v141 offset:23072
	ds_read_b128 v[230:233], v140 offset:4640
	s_waitcnt lgkmcnt(4)
	v_mfma_f32_32x32x16_bf16 v[50:65], v[198:201], v[202:205], v[50:65]
	v_mfma_f32_32x32x16_bf16 v[34:49], v[198:201], v[206:209], v[34:49]
	v_mfma_f32_32x32x16_bf16 v[18:33], v[214:217], v[202:205], v[18:33]
	v_mfma_f32_32x32x16_bf16 v[2:17], v[214:217], v[206:209], v[2:17]
	global_load_dwordx4 v[98:101], v[160:161], off offset:1792
	global_load_dwordx4 v[102:105], v[162:163], off offset:1792
	global_load_dwordx4 v[106:109], v[164:165], off offset:1792
	global_load_dwordx4 v[110:113], v[166:167], off offset:1792
	global_load_dwordx4 v[114:117], v[158:159], off offset:1792
	global_load_dwordx4 v[118:121], v[168:169], off offset:1792
	global_load_dwordx4 v[122:125], v[170:171], off offset:1792
	global_load_dwordx4 v[126:129], v[172:173], off offset:1792
	ds_read_b128 v[198:201], v140 offset:64
	ds_read_b128 v[202:205], v141 offset:18496
	ds_read_b128 v[206:209], v141 offset:23104
	ds_read_b128 v[214:217], v140 offset:4672
	s_waitcnt lgkmcnt(4)
	v_mfma_f32_32x32x16_bf16 v[50:65], v[218:221], v[222:225], v[50:65]
	v_mfma_f32_32x32x16_bf16 v[34:49], v[218:221], v[226:229], v[34:49]
	v_mfma_f32_32x32x16_bf16 v[18:33], v[230:233], v[222:225], v[18:33]
	v_mfma_f32_32x32x16_bf16 v[2:17], v[230:233], v[226:229], v[2:17]
	s_waitcnt vmcnt(8)
	ds_write_b128 v188, v[66:69] offset:36864
	ds_write_b128 v188, v[70:73] offset:41472
	ds_write_b128 v188, v[74:77] offset:46080
	ds_write_b128 v188, v[78:81] offset:50688
	ds_read_b128 v[218:221], v140 offset:96
	ds_read_b128 v[222:225], v141 offset:18528
	ds_read_b128 v[226:229], v141 offset:23136
	ds_read_b128 v[230:233], v140 offset:4704
	s_waitcnt lgkmcnt(4)
	v_mfma_f32_32x32x16_bf16 v[50:65], v[198:201], v[202:205], v[50:65]
	v_mfma_f32_32x32x16_bf16 v[34:49], v[198:201], v[206:209], v[34:49]
	v_mfma_f32_32x32x16_bf16 v[18:33], v[214:217], v[202:205], v[18:33]
	v_mfma_f32_32x32x16_bf16 v[2:17], v[214:217], v[206:209], v[2:17]
	ds_write_b128 v188, v[82:85] offset:55296
	ds_write_b128 v188, v[86:89] offset:59904
	ds_write_b128 v188, v[90:93] offset:64512
	ds_write_b128 v189, v[94:97] offset:13824
	s_waitcnt lgkmcnt(0)
	v_mfma_f32_32x32x16_bf16 v[50:65], v[218:221], v[222:225], v[50:65]
	v_mfma_f32_32x32x16_bf16 v[34:49], v[218:221], v[226:229], v[34:49]
	v_mfma_f32_32x32x16_bf16 v[18:33], v[230:233], v[222:225], v[18:33]
	v_mfma_f32_32x32x16_bf16 v[2:17], v[230:233], v[226:229], v[2:17]
	s_setprio 0
	s_waitcnt lgkmcnt(0)
	s_barrier
; __device__ __forceinline__ void gemm_kstep(const u16* sb, int wn, int wt, int r, int h, f32x16 (&acc)[2][2]) {
;   const u16* bw = sb + (wn * 64 + r) * LDT + h * 8;
;   const u16* bx = sb + TILE_U16 + (wt * 64 + r) * LDT + h * 8;
;   __builtin_amdgcn_s_setprio(1);
; #pragma unroll
;   for (int ks = 0; ks < 4; ++ks) {
;     bf16x8 a0 = *(const bf16x8*)(bw + ks * 16);
;     bf16x8 a1 = *(const bf16x8*)(bw + 32 * LDT + ks * 16);
;     bf16x8 b0 = *(const bf16x8*)(bx + ks * 16);
;     bf16x8 b1 = *(const bf16x8*)(bx + 32 * LDT + ks * 16);
;     acc[0][0] = mfma32(a0, b0, acc[0][0]);
;     acc[0][1] = mfma32(a0, b1, acc[0][1]);
;     acc[1][0] = mfma32(a1, b0, acc[1][0]);
;     acc[1][1] = mfma32(a1, b1, acc[1][1]);
;   }
;   __builtin_amdgcn_s_setprio(0);
; }
; __device__ void gemm_phase(const u16* __restrict__ Wb, int ldw, const u16* __restrict__ Xb, int ldx, int K,
;                            u16* __restrict__ outb, int ldo, int ntn, int ntiles, u16* lds) {
;     ...
;     for (int kt = 0; kt < nk; kt += 2) {
;       if (kt + 2 < nk) gs_load(B, gw, ldw, gx, ldx, (kt + 2) * 64);
;       else if (has_next) gs_load(B, gwn, ldw, gxn, ldx, 0);
;       gemm_kstep(lds, wn, wt, r, h, acc);
;       gs_store(A, lds + 2 * TILE_U16, lo);
;       __syncthreads();
;       if (kt + 3 < nk) gs_load(A, gw, ldw, gx, ldx, (kt + 3) * 64);
;       else if (has_next) gs_load(A, gwn, ldw, gxn, ldx, 64);
;       gemm_kstep(lds + 2 * TILE_U16, wn, wt, r, h, acc);
;       if (kt + 2 < nk) gs_store(B, lds, lo);
;       __syncthreads();
;     }
	global_load_dwordx4 v[66:69], v[160:161], off offset:1920
	global_load_dwordx4 v[70:73], v[162:163], off offset:1920
	global_load_dwordx4 v[74:77], v[164:165], off offset:1920
	global_load_dwordx4 v[78:81], v[166:167], off offset:1920
	global_load_dwordx4 v[82:85], v[158:159], off offset:1920
	global_load_dwordx4 v[86:89], v[168:169], off offset:1920
	global_load_dwordx4 v[90:93], v[170:171], off offset:1920
	global_load_dwordx4 v[94:97], v[172:173], off offset:1920
	s_setprio 1
	ds_read_b128 v[158:161], v140 offset:36864
	ds_read_b128 v[162:165], v141 offset:55296
	ds_read_b128 v[166:169], v141 offset:59904
	ds_read_b128 v[214:217], v140 offset:41472
	ds_read_b128 v[218:221], v140 offset:36896
	ds_read_b128 v[222:225], v141 offset:55328
	ds_read_b128 v[226:229], v141 offset:59936
	ds_read_b128 v[230:233], v140 offset:41504
	s_waitcnt lgkmcnt(4)
	v_mfma_f32_32x32x16_bf16 v[50:65], v[158:161], v[162:165], v[50:65]
	v_mfma_f32_32x32x16_bf16 v[34:49], v[158:161], v[166:169], v[34:49]
	v_mfma_f32_32x32x16_bf16 v[18:33], v[214:217], v[162:165], v[18:33]
	v_mfma_f32_32x32x16_bf16 v[2:17], v[214:217], v[166:169], v[2:17]
	ds_read_b128 v[158:161], v140 offset:36928
	ds_read_b128 v[162:165], v141 offset:55360
	ds_read_b128 v[166:169], v141 offset:59968
	ds_read_b128 v[214:217], v140 offset:41536
	s_waitcnt lgkmcnt(4)
	v_mfma_f32_32x32x16_bf16 v[50:65], v[218:221], v[222:225], v[50:65]
	v_mfma_f32_32x32x16_bf16 v[34:49], v[218:221], v[226:229], v[34:49]
	v_mfma_f32_32x32x16_bf16 v[18:33], v[230:233], v[222:225], v[18:33]
	v_mfma_f32_32x32x16_bf16 v[2:17], v[230:233], v[226:229], v[2:17]
	ds_read_b128 v[218:221], v140 offset:36960
	ds_read_b128 v[222:225], v141 offset:55392
	ds_read_b128 v[226:229], v141 offset:60000
	ds_read_b128 v[230:233], v140 offset:41568
	s_waitcnt lgkmcnt(4)
	v_mfma_f32_32x32x16_bf16 v[50:65], v[158:161], v[162:165], v[50:65]
	v_mfma_f32_32x32x16_bf16 v[34:49], v[158:161], v[166:169], v[34:49]
	v_mfma_f32_32x32x16_bf16 v[18:33], v[214:217], v[162:165], v[18:33]
	v_mfma_f32_32x32x16_bf16 v[2:17], v[214:217], v[166:169], v[2:17]
	s_waitcnt lgkmcnt(0)
	v_mfma_f32_32x32x16_bf16 v[50:65], v[218:221], v[222:225], v[50:65]
	v_mfma_f32_32x32x16_bf16 v[34:49], v[218:221], v[226:229], v[34:49]
	v_mfma_f32_32x32x16_bf16 v[18:33], v[230:233], v[222:225], v[18:33]
	v_mfma_f32_32x32x16_bf16 v[2:17], v[230:233], v[226:229], v[2:17]
	s_setprio 0
	s_and_b64 vcc, exec, s[16:17]
	s_waitcnt vmcnt(8)
	ds_write_b128 v188, v[98:101]
	ds_write_b128 v188, v[102:105] offset:4608
	ds_write_b128 v188, v[106:109] offset:9216
	ds_write_b128 v188, v[110:113] offset:13824
	ds_write_b128 v188, v[114:117] offset:18432
	ds_write_b128 v188, v[118:121] offset:23040
	ds_write_b128 v188, v[122:125] offset:27648
	ds_write_b128 v188, v[126:129] offset:32256
	s_waitcnt lgkmcnt(0)
	s_barrier
	s_cbranch_vccnz .LBB0_600
	v_add_co_u32_e32 v102, vcc, 0x10000, v132
	global_load_dwordx4 v[98:101], v[132:133], off
	s_nop 0
	v_addc_co_u32_e32 v103, vcc, 0, v133, vcc
	v_add_co_u32_e32 v106, vcc, 0x20000, v132
	s_nop 1
	v_addc_co_u32_e32 v107, vcc, 0, v133, vcc
	v_add_co_u32_e32 v110, vcc, 0x30000, v132
	global_load_dwordx4 v[102:105], v[102:103], off
	s_nop 0
	global_load_dwordx4 v[106:109], v[106:107], off
	v_addc_co_u32_e32 v111, vcc, 0, v133, vcc
	v_add_co_u32_e32 v118, vcc, 0x10000, v134
	global_load_dwordx4 v[110:113], v[110:111], off
	s_nop 0
	global_load_dwordx4 v[114:117], v[134:135], off
	v_addc_co_u32_e32 v119, vcc, 0, v135, vcc
	v_add_co_u32_e32 v122, vcc, 0x20000, v134
	s_nop 1
	v_addc_co_u32_e32 v123, vcc, 0, v135, vcc
	v_add_co_u32_e32 v126, vcc, 0x30000, v134
	global_load_dwordx4 v[118:121], v[118:119], off
	s_nop 0
	global_load_dwordx4 v[122:125], v[122:123], off
	v_addc_co_u32_e32 v127, vcc, 0, v135, vcc
	global_load_dwordx4 v[126:129], v[126:127], off

; __device__ __forceinline__ void gemm_kstep(const u16* sb, int wn, int wt, int r, int h, f32x16 (&acc)[2][2]) {
;   const u16* bw = sb + (wn * 64 + r) * LDT + h * 8;
;   const u16* bx = sb + TILE_U16 + (wt * 64 + r) * LDT + h * 8;
;   __builtin_amdgcn_s_setprio(1);
; #pragma unroll
;   for (int ks = 0; ks < 4; ++ks) {
;     bf16x8 a0 = *(const bf16x8*)(bw + ks * 16);
;     bf16x8 a1 = *(const bf16x8*)(bw + 32 * LDT + ks * 16);
;     bf16x8 b0 = *(const bf16x8*)(bx + ks * 16);
;     bf16x8 b1 = *(const bf16x8*)(bx + 32 * LDT + ks * 16);
;     acc[0][0] = mfma32(a0, b0, acc[0][0]);
;     acc[0][1] = mfma32(a0, b1, acc[0][1]);
;     acc[1][0] = mfma32(a1, b0, acc[1][0]);
;     acc[1][1] = mfma32(a1, b1, acc[1][1]);
;   }
;   __builtin_amdgcn_s_setprio(0);
; }
; __device__ void gemm_phase(const u16* __restrict__ Wb, int ldw, const u16* __restrict__ Xb, int ldx, int K,
;                            u16* __restrict__ outb, int ldo, int ntn, int ntiles, u16* lds) {
;     ...
;   for (; q < L; q += nbl) {
;     const int qn = q + nbl;
;     const bool has_next = qn < L;
;     const int qq = has_next ? qn : q;
;     const u16* gwn = Wb + (size_t)(GP_NT(qq) * 128 + lrow) * ldw + lc * 8;
;     const u16* gxn = Xb + (size_t)(GP_MT(qq) * 128 + lrow) * ldx + lc * 8;
;     f32x16 acc[2][2];
; #pragma unroll
;     for (int a = 0; a < 2; ++a)
; #pragma unroll
;       for (int b = 0; b < 2; ++b)
; #pragma unroll
;         for (int i = 0; i < 16; ++i) acc[a][b][i] = 0.f;
;     gs_store(B, lds, lo);
;     __syncthreads();
;     for (int kt = 0; kt < nk; kt += 2) {
;       if (kt + 2 < nk) gs_load(B, gw, ldw, gx, ldx, (kt + 2) * 64);
;       else if (has_next) gs_load(B, gwn, ldw, gxn, ldx, 0);
;       gemm_kstep(lds, wn, wt, r, h, acc);
;       gs_store(A, lds + 2 * TILE_U16, lo);
;       __syncthreads();
.LBB0_609:
	v_mov_b64_e32 v[160:161], v[132:133]
	v_add_co_u32_e32 v162, vcc, s81, v160
	v_mov_b64_e32 v[158:159], v[134:135]
	s_nop 0
	v_addc_co_u32_e32 v163, vcc, 0, v161, vcc
	v_add_co_u32_e32 v164, vcc, s80, v160
	s_waitcnt vmcnt(1)
	ds_write_b128 v188, v[86:89]
	ds_write_b128 v188, v[98:101] offset:4608
	ds_write_b128 v188, v[102:105] offset:9216
	ds_write_b128 v188, v[110:113] offset:13824
	ds_write_b128 v188, v[114:117] offset:18432
	ds_write_b128 v188, v[118:121] offset:23040
	ds_write_b128 v188, v[122:125] offset:27648
	ds_write_b128 v188, v[126:129] offset:32256
	v_addc_co_u32_e32 v165, vcc, 0, v161, vcc
	v_add_co_u32_e32 v166, vcc, s84, v160
	s_waitcnt lgkmcnt(0)
	s_nop 0
	v_addc_co_u32_e32 v167, vcc, 0, v161, vcc
	v_add_co_u32_e32 v168, vcc, s81, v158
	s_barrier
	s_nop 0
	v_addc_co_u32_e32 v169, vcc, 0, v159, vcc
	v_add_co_u32_e32 v170, vcc, s80, v158
	s_nop 1
	v_addc_co_u32_e32 v171, vcc, 0, v159, vcc
	v_add_co_u32_e32 v172, vcc, s84, v158
	global_load_dwordx4 v[86:89], v[132:133], off offset:256
	s_nop 0
	v_addc_co_u32_e32 v173, vcc, 0, v159, vcc
	global_load_dwordx4 v[98:101], v[162:163], off offset:256
	global_load_dwordx4 v[102:105], v[164:165], off offset:256
	global_load_dwordx4 v[110:113], v[166:167], off offset:256
	global_load_dwordx4 v[114:117], v[134:135], off offset:256
	global_load_dwordx4 v[118:121], v[168:169], off offset:256
	global_load_dwordx4 v[122:125], v[170:171], off offset:256
	global_load_dwordx4 v[126:129], v[172:173], off offset:256
	s_add_i32 s42, s41, s87
	s_cmpk_gt_u32 s42, 0xff
	s_cselect_b64 s[0:1], -1, 0
	s_cmpk_lt_u32 s42, 0x100
	s_cselect_b64 s[38:39], -1, 0
	s_and_b64 s[44:45], s[38:39], exec
	s_cselect_b32 s43, s42, s41
	s_lshl_b32 s44, s43, 4
	s_and_b32 s43, s43, 7
	s_or_b32 s43, s43, s18
	s_and_b32 s45, s44, 0x380
	s_and_b32 s44, s44, 0xfffffc00
	s_lshl_b32 s43, s43, 7
	s_add_i32 s43, s43, s44
	v_add_u32_e32 v2, s45, v131
	v_add_u32_e32 v4, s43, v131
	v_ashrrev_i32_e32 v3, 31, v2
	v_ashrrev_i32_e32 v5, 31, v4
	v_lshlrev_b64 v[2:3], 11, v[2:3]
	v_lshlrev_b64 v[4:5], 11, v[4:5]
	v_lshl_add_u64 v[132:133], v[136:137], 0, v[2:3]
	v_lshl_add_u64 v[134:135], v[138:139], 0, v[4:5]
	s_setprio 1
	ds_read_b128 v[2:5], v140
	ds_read_b128 v[6:9], v141 offset:18432
	ds_read_b128 v[10:13], v141 offset:23040
	s_waitcnt lgkmcnt(1)
	v_mfma_f32_32x32x16_bf16 v[50:65], v[2:5], v[6:9], 0
	s_waitcnt lgkmcnt(0)
	v_mfma_f32_32x32x16_bf16 v[34:49], v[2:5], v[10:13], 0
	ds_read_b128 v[2:5], v140 offset:4608
	ds_read_b128 v[198:201], v140 offset:32
	ds_read_b128 v[202:205], v141 offset:18464
	ds_read_b128 v[206:209], v141 offset:23072
	s_waitcnt lgkmcnt(1)
	v_mfma_f32_32x32x16_bf16 v[50:65], v[198:201], v[202:205], v[50:65]
	s_waitcnt lgkmcnt(0)
	v_mfma_f32_32x32x16_bf16 v[34:49], v[198:201], v[206:209], v[34:49]
	ds_read_b128 v[198:201], v140 offset:4640
	v_mfma_f32_32x32x16_bf16 v[18:33], v[2:5], v[6:9], 0
	v_mfma_f32_32x32x16_bf16 v[2:17], v[2:5], v[10:13], 0
	s_waitcnt lgkmcnt(0)
	v_mfma_f32_32x32x16_bf16 v[18:33], v[198:201], v[202:205], v[18:33]
	v_mfma_f32_32x32x16_bf16 v[2:17], v[198:201], v[206:209], v[2:17]
	ds_read_b128 v[198:201], v140 offset:64
	ds_read_b128 v[202:205], v141 offset:18496
	ds_read_b128 v[206:209], v141 offset:23104
	s_waitcnt lgkmcnt(1)
	v_mfma_f32_32x32x16_bf16 v[50:65], v[198:201], v[202:205], v[50:65]
	s_waitcnt lgkmcnt(0)
	v_mfma_f32_32x32x16_bf16 v[34:49], v[198:201], v[206:209], v[34:49]
	ds_read_b128 v[198:201], v140 offset:4672
	s_waitcnt lgkmcnt(0)
	v_mfma_f32_32x32x16_bf16 v[18:33], v[198:201], v[202:205], v[18:33]
	v_mfma_f32_32x32x16_bf16 v[2:17], v[198:201], v[206:209], v[2:17]
	ds_read_b128 v[198:201], v140 offset:96
	ds_read_b128 v[202:205], v141 offset:18528
	ds_read_b128 v[206:209], v141 offset:23136
	s_waitcnt lgkmcnt(1)
	v_mfma_f32_32x32x16_bf16 v[50:65], v[198:201], v[202:205], v[50:65]
	s_waitcnt lgkmcnt(0)
	v_mfma_f32_32x32x16_bf16 v[34:49], v[198:201], v[206:209], v[34:49]
	ds_read_b128 v[198:201], v140 offset:4704
	s_waitcnt lgkmcnt(0)
	v_mfma_f32_32x32x16_bf16 v[18:33], v[198:201], v[202:205], v[18:33]
	v_mfma_f32_32x32x16_bf16 v[2:17], v[198:201], v[206:209], v[2:17]
	s_setprio 0
	ds_write_b128 v188, v[66:69] offset:36864
	ds_write_b128 v188, v[70:73] offset:41472
	ds_write_b128 v188, v[74:77] offset:46080
	ds_write_b128 v188, v[78:81] offset:50688
	ds_write_b128 v188, v[82:85] offset:55296
	ds_write_b128 v188, v[90:93] offset:59904
	ds_write_b128 v188, v[94:97] offset:64512
	s_waitcnt vmcnt(8)
	ds_write_b128 v189, v[106:109] offset:13824
	s_waitcnt lgkmcnt(0)
	s_barrier
; __device__ __forceinline__ void gemm_kstep(const u16* sb, int wn, int wt, int r, int h, f32x16 (&acc)[2][2]) {
;   const u16* bw = sb + (wn * 64 + r) * LDT + h * 8;
;   const u16* bx = sb + TILE_U16 + (wt * 64 + r) * LDT + h * 8;
;   __builtin_amdgcn_s_setprio(1);
; #pragma unroll
;   for (int ks = 0; ks < 4; ++ks) {
;     bf16x8 a0 = *(const bf16x8*)(bw + ks * 16);
;     bf16x8 a1 = *(const bf16x8*)(bw + 32 * LDT + ks * 16);
;     bf16x8 b0 = *(const bf16x8*)(bx + ks * 16);
;     bf16x8 b1 = *(const bf16x8*)(bx + 32 * LDT + ks * 16);
;     acc[0][0] = mfma32(a0, b0, acc[0][0]);
;     acc[0][1] = mfma32(a0, b1, acc[0][1]);
;     acc[1][0] = mfma32(a1, b0, acc[1][0]);
;     acc[1][1] = mfma32(a1, b1, acc[1][1]);
;   }
;   __builtin_amdgcn_s_setprio(0);
; }
; __device__ void gemm_phase(const u16* __restrict__ Wb, int ldw, const u16* __restrict__ Xb, int ldx, int K,
;                            u16* __restrict__ outb, int ldo, int ntn, int ntiles, u16* lds) {
;     ...
;     for (int kt = 0; kt < nk; kt += 2) {
;       if (kt + 2 < nk) gs_load(B, gw, ldw, gx, ldx, (kt + 2) * 64);
;       else if (has_next) gs_load(B, gwn, ldw, gxn, ldx, 0);
;       gemm_kstep(lds, wn, wt, r, h, acc);
;       gs_store(A, lds + 2 * TILE_U16, lo);
;       __syncthreads();
;       if (kt + 3 < nk) gs_load(A, gw, ldw, gx, ldx, (kt + 3) * 64);
;       else if (has_next) gs_load(A, gwn, ldw, gxn, ldx, 64);
;       gemm_kstep(lds + 2 * TILE_U16, wn, wt, r, h, acc);
;       if (kt + 2 < nk) gs_store(B, lds, lo);
;       __syncthreads();
;     }
	s_setprio 1
	ds_read_b128 v[198:201], v140 offset:36864
	ds_read_b128 v[202:205], v141 offset:55296
	ds_read_b128 v[206:209], v141 offset:59904
	ds_read_b128 v[214:217], v140 offset:41472
	ds_read_b128 v[218:221], v140 offset:36896
	ds_read_b128 v[222:225], v141 offset:55328
	ds_read_b128 v[226:229], v141 offset:59936
	ds_read_b128 v[230:233], v140 offset:41504
	s_waitcnt lgkmcnt(4)
	v_mfma_f32_32x32x16_bf16 v[50:65], v[198:201], v[202:205], v[50:65]
	v_mfma_f32_32x32x16_bf16 v[34:49], v[198:201], v[206:209], v[34:49]
	v_mfma_f32_32x32x16_bf16 v[18:33], v[214:217], v[202:205], v[18:33]
	v_mfma_f32_32x32x16_bf16 v[2:17], v[214:217], v[206:209], v[2:17]
	global_load_dwordx4 v[66:69], v[160:161], off offset:384
	global_load_dwordx4 v[70:73], v[162:163], off offset:384
	global_load_dwordx4 v[74:77], v[164:165], off offset:384
	global_load_dwordx4 v[78:81], v[166:167], off offset:384
	global_load_dwordx4 v[82:85], v[158:159], off offset:384
	global_load_dwordx4 v[90:93], v[168:169], off offset:384
	global_load_dwordx4 v[94:97], v[170:171], off offset:384
	global_load_dwordx4 v[106:109], v[172:173], off offset:384
	ds_read_b128 v[198:201], v140 offset:36928
	ds_read_b128 v[202:205], v141 offset:55360
	ds_read_b128 v[206:209], v141 offset:59968
	ds_read_b128 v[214:217], v140 offset:41536
	s_waitcnt lgkmcnt(4)
	v_mfma_f32_32x32x16_bf16 v[50:65], v[218:221], v[222:225], v[50:65]
	v_mfma_f32_32x32x16_bf16 v[34:49], v[218:221], v[226:229], v[34:49]
	v_mfma_f32_32x32x16_bf16 v[18:33], v[230:233], v[222:225], v[18:33]
	v_mfma_f32_32x32x16_bf16 v[2:17], v[230:233], v[226:229], v[2:17]
	s_waitcnt vmcnt(8)
	ds_write_b128 v188, v[86:89]
	ds_write_b128 v188, v[98:101] offset:4608
	ds_write_b128 v188, v[102:105] offset:9216
	ds_write_b128 v188, v[110:113] offset:13824
	ds_read_b128 v[218:221], v140 offset:36960
	ds_read_b128 v[222:225], v141 offset:55392
	ds_read_b128 v[226:229], v141 offset:60000
	ds_read_b128 v[230:233], v140 offset:41568
	s_waitcnt lgkmcnt(4)
	v_mfma_f32_32x32x16_bf16 v[50:65], v[198:201], v[202:205], v[50:65]
	v_mfma_f32_32x32x16_bf16 v[34:49], v[198:201], v[206:209], v[34:49]
	v_mfma_f32_32x32x16_bf16 v[18:33], v[214:217], v[202:205], v[18:33]
	v_mfma_f32_32x32x16_bf16 v[2:17], v[214:217], v[206:209], v[2:17]
	ds_write_b128 v188, v[114:117] offset:18432
	ds_write_b128 v188, v[118:121] offset:23040
	ds_write_b128 v188, v[122:125] offset:27648
	ds_write_b128 v188, v[126:129] offset:32256
	s_waitcnt lgkmcnt(0)
	v_mfma_f32_32x32x16_bf16 v[50:65], v[218:221], v[222:225], v[50:65]
	v_mfma_f32_32x32x16_bf16 v[34:49], v[218:221], v[226:229], v[34:49]
	v_mfma_f32_32x32x16_bf16 v[18:33], v[230:233], v[222:225], v[18:33]
	v_mfma_f32_32x32x16_bf16 v[2:17], v[230:233], v[226:229], v[2:17]
	s_setprio 0
	s_waitcnt lgkmcnt(0)
	s_barrier
	s_setprio 1
	ds_read_b128 v[198:201], v140
	ds_read_b128 v[202:205], v141 offset:18432
	ds_read_b128 v[206:209], v141 offset:23040
	ds_read_b128 v[214:217], v140 offset:4608
	ds_read_b128 v[218:221], v140 offset:32
	ds_read_b128 v[222:225], v141 offset:18464
	ds_read_b128 v[226:229], v141 offset:23072
	ds_read_b128 v[230:233], v140 offset:4640
	s_waitcnt lgkmcnt(4)
	v_mfma_f32_32x32x16_bf16 v[50:65], v[198:201], v[202:205], v[50:65]
	v_mfma_f32_32x32x16_bf16 v[34:49], v[198:201], v[206:209], v[34:49]
	v_mfma_f32_32x32x16_bf16 v[18:33], v[214:217], v[202:205], v[18:33]
	v_mfma_f32_32x32x16_bf16 v[2:17], v[214:217], v[206:209], v[2:17]
	global_load_dwordx4 v[86:89], v[160:161], off offset:512
	global_load_dwordx4 v[98:101], v[162:163], off offset:512
	global_load_dwordx4 v[102:105], v[164:165], off offset:512
	global_load_dwordx4 v[110:113], v[166:167], off offset:512
	global_load_dwordx4 v[114:117], v[158:159], off offset:512
	global_load_dwordx4 v[118:121], v[168:169], off offset:512
	global_load_dwordx4 v[122:125], v[170:171], off offset:512
	global_load_dwordx4 v[126:129], v[172:173], off offset:512
	ds_read_b128 v[198:201], v140 offset:64
	ds_read_b128 v[202:205], v141 offset:18496
	ds_read_b128 v[206:209], v141 offset:23104
	ds_read_b128 v[214:217], v140 offset:4672
	s_waitcnt lgkmcnt(4)
	v_mfma_f32_32x32x16_bf16 v[50:65], v[218:221], v[222:225], v[50:65]
	v_mfma_f32_32x32x16_bf16 v[34:49], v[218:221], v[226:229], v[34:49]
	v_mfma_f32_32x32x16_bf16 v[18:33], v[230:233], v[222:225], v[18:33]
	v_mfma_f32_32x32x16_bf16 v[2:17], v[230:233], v[226:229], v[2:17]
	s_waitcnt vmcnt(8)
	ds_write_b128 v188, v[66:69] offset:36864
	ds_write_b128 v188, v[70:73] offset:41472
	ds_write_b128 v188, v[74:77] offset:46080
	ds_write_b128 v188, v[78:81] offset:50688
	ds_read_b128 v[218:221], v140 offset:96
	ds_read_b128 v[222:225], v141 offset:18528
	ds_read_b128 v[226:229], v141 offset:23136
	ds_read_b128 v[230:233], v140 offset:4704
	s_waitcnt lgkmcnt(4)
	v_mfma_f32_32x32x16_bf16 v[50:65], v[198:201], v[202:205], v[50:65]
	v_mfma_f32_32x32x16_bf16 v[34:49], v[198:201], v[206:209], v[34:49]
	v_mfma_f32_32x32x16_bf16 v[18:33], v[214:217], v[202:205], v[18:33]
	v_mfma_f32_32x32x16_bf16 v[2:17], v[214:217], v[206:209], v[2:17]
	ds_write_b128 v188, v[82:85] offset:55296
	ds_write_b128 v188, v[90:93] offset:59904
	ds_write_b128 v188, v[94:97] offset:64512
	ds_write_b128 v189, v[106:109] offset:13824
	s_waitcnt lgkmcnt(0)
	v_mfma_f32_32x32x16_bf16 v[50:65], v[218:221], v[222:225], v[50:65]
	v_mfma_f32_32x32x16_bf16 v[34:49], v[218:221], v[226:229], v[34:49]
	v_mfma_f32_32x32x16_bf16 v[18:33], v[230:233], v[222:225], v[18:33]
	v_mfma_f32_32x32x16_bf16 v[2:17], v[230:233], v[226:229], v[2:17]
	s_setprio 0
	s_waitcnt lgkmcnt(0)
	s_barrier
; __device__ __forceinline__ void gemm_kstep(const u16* sb, int wn, int wt, int r, int h, f32x16 (&acc)[2][2]) {
;   const u16* bw = sb + (wn * 64 + r) * LDT + h * 8;
;   const u16* bx = sb + TILE_U16 + (wt * 64 + r) * LDT + h * 8;
;   __builtin_amdgcn_s_setprio(1);
; #pragma unroll
;   for (int ks = 0; ks < 4; ++ks) {
;     bf16x8 a0 = *(const bf16x8*)(bw + ks * 16);
;     bf16x8 a1 = *(const bf16x8*)(bw + 32 * LDT + ks * 16);
;     bf16x8 b0 = *(const bf16x8*)(bx + ks * 16);
;     bf16x8 b1 = *(const bf16x8*)(bx + 32 * LDT + ks * 16);
;     acc[0][0] = mfma32(a0, b0, acc[0][0]);
;     acc[0][1] = mfma32(a0, b1, acc[0][1]);
;     acc[1][0] = mfma32(a1, b0, acc[1][0]);
;     acc[1][1] = mfma32(a1, b1, acc[1][1]);
;   }
;   __builtin_amdgcn_s_setprio(0);
; }
; __device__ void gemm_phase(const u16* __restrict__ Wb, int ldw, const u16* __restrict__ Xb, int ldx, int K,
;                            u16* __restrict__ outb, int ldo, int ntn, int ntiles, u16* lds) {
;     ...
;     for (int kt = 0; kt < nk; kt += 2) {
;       if (kt + 2 < nk) gs_load(B, gw, ldw, gx, ldx, (kt + 2) * 64);
;       else if (has_next) gs_load(B, gwn, ldw, gxn, ldx, 0);
;       gemm_kstep(lds, wn, wt, r, h, acc);
;       gs_store(A, lds + 2 * TILE_U16, lo);
;       __syncthreads();
;       if (kt + 3 < nk) gs_load(A, gw, ldw, gx, ldx, (kt + 3) * 64);
;       else if (has_next) gs_load(A, gwn, ldw, gxn, ldx, 64);
;       gemm_kstep(lds + 2 * TILE_U16, wn, wt, r, h, acc);
;       if (kt + 2 < nk) gs_store(B, lds, lo);
;       __syncthreads();
;     }
	s_setprio 1
	ds_read_b128 v[198:201], v140 offset:36864
	ds_read_b128 v[202:205], v141 offset:55296
	ds_read_b128 v[206:209], v141 offset:59904
	ds_read_b128 v[214:217], v140 offset:41472
	ds_read_b128 v[218:221], v140 offset:36896
	ds_read_b128 v[222:225], v141 offset:55328
	ds_read_b128 v[226:229], v141 offset:59936
	ds_read_b128 v[230:233], v140 offset:41504
	s_waitcnt lgkmcnt(4)
	v_mfma_f32_32x32x16_bf16 v[50:65], v[198:201], v[202:205], v[50:65]
	v_mfma_f32_32x32x16_bf16 v[34:49], v[198:201], v[206:209], v[34:49]
	v_mfma_f32_32x32x16_bf16 v[18:33], v[214:217], v[202:205], v[18:33]
	v_mfma_f32_32x32x16_bf16 v[2:17], v[214:217], v[206:209], v[2:17]
	global_load_dwordx4 v[66:69], v[160:161], off offset:640
	global_load_dwordx4 v[70:73], v[162:163], off offset:640
	global_load_dwordx4 v[74:77], v[164:165], off offset:640
	global_load_dwordx4 v[78:81], v[166:167], off offset:640
	global_load_dwordx4 v[82:85], v[158:159], off offset:640
	global_load_dwordx4 v[90:93], v[168:169], off offset:640
	global_load_dwordx4 v[94:97], v[170:171], off offset:640
	global_load_dwordx4 v[106:109], v[172:173], off offset:640
	ds_read_b128 v[198:201], v140 offset:36928
	ds_read_b128 v[202:205], v141 offset:55360
	ds_read_b128 v[206:209], v141 offset:59968
	ds_read_b128 v[214:217], v140 offset:41536
	s_waitcnt lgkmcnt(4)
	v_mfma_f32_32x32x16_bf16 v[50:65], v[218:221], v[222:225], v[50:65]
	v_mfma_f32_32x32x16_bf16 v[34:49], v[218:221], v[226:229], v[34:49]
	v_mfma_f32_32x32x16_bf16 v[18:33], v[230:233], v[222:225], v[18:33]
	v_mfma_f32_32x32x16_bf16 v[2:17], v[230:233], v[226:229], v[2:17]
	s_waitcnt vmcnt(8)
	ds_write_b128 v188, v[86:89]
	ds_write_b128 v188, v[98:101] offset:4608
	ds_write_b128 v188, v[102:105] offset:9216
	ds_write_b128 v188, v[110:113] offset:13824
	ds_read_b128 v[218:221], v140 offset:36960
	ds_read_b128 v[222:225], v141 offset:55392
	ds_read_b128 v[226:229], v141 offset:60000
	ds_read_b128 v[230:233], v140 offset:41568
	s_waitcnt lgkmcnt(4)
	v_mfma_f32_32x32x16_bf16 v[50:65], v[198:201], v[202:205], v[50:65]
	v_mfma_f32_32x32x16_bf16 v[34:49], v[198:201], v[206:209], v[34:49]
	v_mfma_f32_32x32x16_bf16 v[18:33], v[214:217], v[202:205], v[18:33]
	v_mfma_f32_32x32x16_bf16 v[2:17], v[214:217], v[206:209], v[2:17]
	ds_write_b128 v188, v[114:117] offset:18432
	ds_write_b128 v188, v[118:121] offset:23040
	ds_write_b128 v188, v[122:125] offset:27648
	ds_write_b128 v188, v[126:129] offset:32256
	s_waitcnt lgkmcnt(0)
	v_mfma_f32_32x32x16_bf16 v[50:65], v[218:221], v[222:225], v[50:65]
	v_mfma_f32_32x32x16_bf16 v[34:49], v[218:221], v[226:229], v[34:49]
	v_mfma_f32_32x32x16_bf16 v[18:33], v[230:233], v[222:225], v[18:33]
	v_mfma_f32_32x32x16_bf16 v[2:17], v[230:233], v[226:229], v[2:17]
	s_setprio 0
	s_waitcnt lgkmcnt(0)
	s_barrier
	s_setprio 1
	ds_read_b128 v[198:201], v140
	ds_read_b128 v[202:205], v141 offset:18432
	ds_read_b128 v[206:209], v141 offset:23040
	ds_read_b128 v[214:217], v140 offset:4608
	ds_read_b128 v[218:221], v140 offset:32
	ds_read_b128 v[222:225], v141 offset:18464
	ds_read_b128 v[226:229], v141 offset:23072
	ds_read_b128 v[230:233], v140 offset:4640
	s_waitcnt lgkmcnt(4)
	v_mfma_f32_32x32x16_bf16 v[50:65], v[198:201], v[202:205], v[50:65]
	v_mfma_f32_32x32x16_bf16 v[34:49], v[198:201], v[206:209], v[34:49]
	v_mfma_f32_32x32x16_bf16 v[18:33], v[214:217], v[202:205], v[18:33]
	v_mfma_f32_32x32x16_bf16 v[2:17], v[214:217], v[206:209], v[2:17]
	global_load_dwordx4 v[86:89], v[160:161], off offset:768
	global_load_dwordx4 v[98:101], v[162:163], off offset:768
	global_load_dwordx4 v[102:105], v[164:165], off offset:768
	global_load_dwordx4 v[110:113], v[166:167], off offset:768
	global_load_dwordx4 v[114:117], v[158:159], off offset:768
	global_load_dwordx4 v[118:121], v[168:169], off offset:768
	global_load_dwordx4 v[122:125], v[170:171], off offset:768
	global_load_dwordx4 v[126:129], v[172:173], off offset:768
	ds_read_b128 v[198:201], v140 offset:64
	ds_read_b128 v[202:205], v141 offset:18496
	ds_read_b128 v[206:209], v141 offset:23104
	ds_read_b128 v[214:217], v140 offset:4672
	s_waitcnt lgkmcnt(4)
	v_mfma_f32_32x32x16_bf16 v[50:65], v[218:221], v[222:225], v[50:65]
	v_mfma_f32_32x32x16_bf16 v[34:49], v[218:221], v[226:229], v[34:49]
	v_mfma_f32_32x32x16_bf16 v[18:33], v[230:233], v[222:225], v[18:33]
	v_mfma_f32_32x32x16_bf16 v[2:17], v[230:233], v[226:229], v[2:17]
	s_waitcnt vmcnt(8)
	ds_write_b128 v188, v[66:69] offset:36864
	ds_write_b128 v188, v[70:73] offset:41472
	ds_write_b128 v188, v[74:77] offset:46080
	ds_write_b128 v188, v[78:81] offset:50688
	ds_read_b128 v[218:221], v140 offset:96
	ds_read_b128 v[222:225], v141 offset:18528
	ds_read_b128 v[226:229], v141 offset:23136
	ds_read_b128 v[230:233], v140 offset:4704
	s_waitcnt lgkmcnt(4)
	v_mfma_f32_32x32x16_bf16 v[50:65], v[198:201], v[202:205], v[50:65]
	v_mfma_f32_32x32x16_bf16 v[34:49], v[198:201], v[206:209], v[34:49]
	v_mfma_f32_32x32x16_bf16 v[18:33], v[214:217], v[202:205], v[18:33]
	v_mfma_f32_32x32x16_bf16 v[2:17], v[214:217], v[206:209], v[2:17]
	ds_write_b128 v188, v[82:85] offset:55296
	ds_write_b128 v188, v[90:93] offset:59904
	ds_write_b128 v188, v[94:97] offset:64512
	ds_write_b128 v189, v[106:109] offset:13824
	s_waitcnt lgkmcnt(0)
	v_mfma_f32_32x32x16_bf16 v[50:65], v[218:221], v[222:225], v[50:65]
	v_mfma_f32_32x32x16_bf16 v[34:49], v[218:221], v[226:229], v[34:49]
	v_mfma_f32_32x32x16_bf16 v[18:33], v[230:233], v[222:225], v[18:33]
	v_mfma_f32_32x32x16_bf16 v[2:17], v[230:233], v[226:229], v[2:17]
	s_setprio 0
	s_waitcnt lgkmcnt(0)
	s_barrier
; __device__ __forceinline__ void gemm_kstep(const u16* sb, int wn, int wt, int r, int h, f32x16 (&acc)[2][2]) {
;   const u16* bw = sb + (wn * 64 + r) * LDT + h * 8;
;   const u16* bx = sb + TILE_U16 + (wt * 64 + r) * LDT + h * 8;
;   __builtin_amdgcn_s_setprio(1);
; #pragma unroll
;   for (int ks = 0; ks < 4; ++ks) {
;     bf16x8 a0 = *(const bf16x8*)(bw + ks * 16);
;     bf16x8 a1 = *(const bf16x8*)(bw + 32 * LDT + ks * 16);
;     bf16x8 b0 = *(const bf16x8*)(bx + ks * 16);
;     bf16x8 b1 = *(const bf16x8*)(bx + 32 * LDT + ks * 16);
;     acc[0][0] = mfma32(a0, b0, acc[0][0]);
;     acc[0][1] = mfma32(a0, b1, acc[0][1]);
;     acc[1][0] = mfma32(a1, b0, acc[1][0]);
;     acc[1][1] = mfma32(a1, b1, acc[1][1]);
;   }
;   __builtin_amdgcn_s_setprio(0);
; }
; __device__ void gemm_phase(const u16* __restrict__ Wb, int ldw, const u16* __restrict__ Xb, int ldx, int K,
;                            u16* __restrict__ outb, int ldo, int ntn, int ntiles, u16* lds) {
;     ...
;     for (int kt = 0; kt < nk; kt += 2) {
;       if (kt + 2 < nk) gs_load(B, gw, ldw, gx, ldx, (kt + 2) * 64);
;       else if (has_next) gs_load(B, gwn, ldw, gxn, ldx, 0);
;       gemm_kstep(lds, wn, wt, r, h, acc);
;       gs_store(A, lds + 2 * TILE_U16, lo);
;       __syncthreads();
;       if (kt + 3 < nk) gs_load(A, gw, ldw, gx, ldx, (kt + 3) * 64);
;       else if (has_next) gs_load(A, gwn, ldw, gxn, ldx, 64);
;       gemm_kstep(lds + 2 * TILE_U16, wn, wt, r, h, acc);
;       if (kt + 2 < nk) gs_store(B, lds, lo);
;       __syncthreads();
;     }
	s_setprio 1
	ds_read_b128 v[198:201], v140 offset:36864
	ds_read_b128 v[202:205], v141 offset:55296
	ds_read_b128 v[206:209], v141 offset:59904
	ds_read_b128 v[214:217], v140 offset:41472
	ds_read_b128 v[218:221], v140 offset:36896
	ds_read_b128 v[222:225], v141 offset:55328
	ds_read_b128 v[226:229], v141 offset:59936
	ds_read_b128 v[230:233], v140 offset:41504
	s_waitcnt lgkmcnt(4)
	v_mfma_f32_32x32x16_bf16 v[50:65], v[198:201], v[202:205], v[50:65]
	v_mfma_f32_32x32x16_bf16 v[34:49], v[198:201], v[206:209], v[34:49]
	v_mfma_f32_32x32x16_bf16 v[18:33], v[214:217], v[202:205], v[18:33]
	v_mfma_f32_32x32x16_bf16 v[2:17], v[214:217], v[206:209], v[2:17]
	global_load_dwordx4 v[66:69], v[160:161], off offset:896
	global_load_dwordx4 v[70:73], v[162:163], off offset:896
	global_load_dwordx4 v[74:77], v[164:165], off offset:896
	global_load_dwordx4 v[78:81], v[166:167], off offset:896
	global_load_dwordx4 v[82:85], v[158:159], off offset:896
	global_load_dwordx4 v[90:93], v[168:169], off offset:896
	global_load_dwordx4 v[94:97], v[170:171], off offset:896
	global_load_dwordx4 v[106:109], v[172:173], off offset:896
	ds_read_b128 v[198:201], v140 offset:36928
	ds_read_b128 v[202:205], v141 offset:55360
	ds_read_b128 v[206:209], v141 offset:59968
	ds_read_b128 v[214:217], v140 offset:41536
	s_waitcnt lgkmcnt(4)
	v_mfma_f32_32x32x16_bf16 v[50:65], v[218:221], v[222:225], v[50:65]
	v_mfma_f32_32x32x16_bf16 v[34:49], v[218:221], v[226:229], v[34:49]
	v_mfma_f32_32x32x16_bf16 v[18:33], v[230:233], v[222:225], v[18:33]
	v_mfma_f32_32x32x16_bf16 v[2:17], v[230:233], v[226:229], v[2:17]
	s_waitcnt vmcnt(8)
	ds_write_b128 v188, v[86:89]
	ds_write_b128 v188, v[98:101] offset:4608
	ds_write_b128 v188, v[102:105] offset:9216
	ds_write_b128 v188, v[110:113] offset:13824
	ds_read_b128 v[218:221], v140 offset:36960
	ds_read_b128 v[222:225], v141 offset:55392
	ds_read_b128 v[226:229], v141 offset:60000
	ds_read_b128 v[230:233], v140 offset:41568
	s_waitcnt lgkmcnt(4)
	v_mfma_f32_32x32x16_bf16 v[50:65], v[198:201], v[202:205], v[50:65]
	v_mfma_f32_32x32x16_bf16 v[34:49], v[198:201], v[206:209], v[34:49]
	v_mfma_f32_32x32x16_bf16 v[18:33], v[214:217], v[202:205], v[18:33]
	v_mfma_f32_32x32x16_bf16 v[2:17], v[214:217], v[206:209], v[2:17]
	ds_write_b128 v188, v[114:117] offset:18432
	ds_write_b128 v188, v[118:121] offset:23040
	ds_write_b128 v188, v[122:125] offset:27648
	ds_write_b128 v188, v[126:129] offset:32256
	s_waitcnt lgkmcnt(0)
	v_mfma_f32_32x32x16_bf16 v[50:65], v[218:221], v[222:225], v[50:65]
	v_mfma_f32_32x32x16_bf16 v[34:49], v[218:221], v[226:229], v[34:49]
	v_mfma_f32_32x32x16_bf16 v[18:33], v[230:233], v[222:225], v[18:33]
	v_mfma_f32_32x32x16_bf16 v[2:17], v[230:233], v[226:229], v[2:17]
	s_setprio 0
	s_waitcnt lgkmcnt(0)
	s_barrier
	s_setprio 1
	ds_read_b128 v[198:201], v140
	ds_read_b128 v[202:205], v141 offset:18432
	ds_read_b128 v[206:209], v141 offset:23040
	ds_read_b128 v[214:217], v140 offset:4608
	ds_read_b128 v[218:221], v140 offset:32
	ds_read_b128 v[222:225], v141 offset:18464
	ds_read_b128 v[226:229], v141 offset:23072
	ds_read_b128 v[230:233], v140 offset:4640
	s_waitcnt lgkmcnt(4)
	v_mfma_f32_32x32x16_bf16 v[50:65], v[198:201], v[202:205], v[50:65]
	v_mfma_f32_32x32x16_bf16 v[34:49], v[198:201], v[206:209], v[34:49]
	v_mfma_f32_32x32x16_bf16 v[18:33], v[214:217], v[202:205], v[18:33]
	v_mfma_f32_32x32x16_bf16 v[2:17], v[214:217], v[206:209], v[2:17]
	global_load_dwordx4 v[86:89], v[160:161], off offset:1024
	global_load_dwordx4 v[98:101], v[162:163], off offset:1024
	global_load_dwordx4 v[102:105], v[164:165], off offset:1024
	global_load_dwordx4 v[110:113], v[166:167], off offset:1024
	global_load_dwordx4 v[114:117], v[158:159], off offset:1024
	global_load_dwordx4 v[118:121], v[168:169], off offset:1024
	global_load_dwordx4 v[122:125], v[170:171], off offset:1024
	global_load_dwordx4 v[126:129], v[172:173], off offset:1024
	ds_read_b128 v[198:201], v140 offset:64
	ds_read_b128 v[202:205], v141 offset:18496
	ds_read_b128 v[206:209], v141 offset:23104
	ds_read_b128 v[214:217], v140 offset:4672
	s_waitcnt lgkmcnt(4)
	v_mfma_f32_32x32x16_bf16 v[50:65], v[218:221], v[222:225], v[50:65]
	v_mfma_f32_32x32x16_bf16 v[34:49], v[218:221], v[226:229], v[34:49]
	v_mfma_f32_32x32x16_bf16 v[18:33], v[230:233], v[222:225], v[18:33]
	v_mfma_f32_32x32x16_bf16 v[2:17], v[230:233], v[226:229], v[2:17]
	s_waitcnt vmcnt(8)
	ds_write_b128 v188, v[66:69] offset:36864
	ds_write_b128 v188, v[70:73] offset:41472
	ds_write_b128 v188, v[74:77] offset:46080
	ds_write_b128 v188, v[78:81] offset:50688
	ds_read_b128 v[218:221], v140 offset:96
	ds_read_b128 v[222:225], v141 offset:18528
	ds_read_b128 v[226:229], v141 offset:23136
	ds_read_b128 v[230:233], v140 offset:4704
	s_waitcnt lgkmcnt(4)
	v_mfma_f32_32x32x16_bf16 v[50:65], v[198:201], v[202:205], v[50:65]
	v_mfma_f32_32x32x16_bf16 v[34:49], v[198:201], v[206:209], v[34:49]
	v_mfma_f32_32x32x16_bf16 v[18:33], v[214:217], v[202:205], v[18:33]
	v_mfma_f32_32x32x16_bf16 v[2:17], v[214:217], v[206:209], v[2:17]
	ds_write_b128 v188, v[82:85] offset:55296
	ds_write_b128 v188, v[90:93] offset:59904
	ds_write_b128 v188, v[94:97] offset:64512
	ds_write_b128 v189, v[106:109] offset:13824
	s_waitcnt lgkmcnt(0)
	v_mfma_f32_32x32x16_bf16 v[50:65], v[218:221], v[222:225], v[50:65]
	v_mfma_f32_32x32x16_bf16 v[34:49], v[218:221], v[226:229], v[34:49]
	v_mfma_f32_32x32x16_bf16 v[18:33], v[230:233], v[222:225], v[18:33]
	v_mfma_f32_32x32x16_bf16 v[2:17], v[230:233], v[226:229], v[2:17]
	s_setprio 0
	s_waitcnt lgkmcnt(0)
	s_barrier
; __device__ __forceinline__ void gemm_kstep(const u16* sb, int wn, int wt, int r, int h, f32x16 (&acc)[2][2]) {
;   const u16* bw = sb + (wn * 64 + r) * LDT + h * 8;
;   const u16* bx = sb + TILE_U16 + (wt * 64 + r) * LDT + h * 8;
;   __builtin_amdgcn_s_setprio(1);
; #pragma unroll
;   for (int ks = 0; ks < 4; ++ks) {
;     bf16x8 a0 = *(const bf16x8*)(bw + ks * 16);
;     bf16x8 a1 = *(const bf16x8*)(bw + 32 * LDT + ks * 16);
;     bf16x8 b0 = *(const bf16x8*)(bx + ks * 16);
;     bf16x8 b1 = *(const bf16x8*)(bx + 32 * LDT + ks * 16);
;     acc[0][0] = mfma32(a0, b0, acc[0][0]);
;     acc[0][1] = mfma32(a0, b1, acc[0][1]);
;     acc[1][0] = mfma32(a1, b0, acc[1][0]);
;     acc[1][1] = mfma32(a1, b1, acc[1][1]);
;   }
;   __builtin_amdgcn_s_setprio(0);
; }
; __device__ void gemm_phase(const u16* __restrict__ Wb, int ldw, const u16* __restrict__ Xb, int ldx, int K,
;                            u16* __restrict__ outb, int ldo, int ntn, int ntiles, u16* lds) {
;     ...
;     for (int kt = 0; kt < nk; kt += 2) {
;       if (kt + 2 < nk) gs_load(B, gw, ldw, gx, ldx, (kt + 2) * 64);
;       else if (has_next) gs_load(B, gwn, ldw, gxn, ldx, 0);
;       gemm_kstep(lds, wn, wt, r, h, acc);
;       gs_store(A, lds + 2 * TILE_U16, lo);
;       __syncthreads();
;       if (kt + 3 < nk) gs_load(A, gw, ldw, gx, ldx, (kt + 3) * 64);
;       else if (has_next) gs_load(A, gwn, ldw, gxn, ldx, 64);
;       gemm_kstep(lds + 2 * TILE_U16, wn, wt, r, h, acc);
;       if (kt + 2 < nk) gs_store(B, lds, lo);
;       __syncthreads();
;     }
	s_setprio 1
	ds_read_b128 v[198:201], v140 offset:36864
	ds_read_b128 v[202:205], v141 offset:55296
	ds_read_b128 v[206:209], v141 offset:59904
	ds_read_b128 v[214:217], v140 offset:41472
	ds_read_b128 v[218:221], v140 offset:36896
	ds_read_b128 v[222:225], v141 offset:55328
	ds_read_b128 v[226:229], v141 offset:59936
	ds_read_b128 v[230:233], v140 offset:41504
	s_waitcnt lgkmcnt(4)
	v_mfma_f32_32x32x16_bf16 v[50:65], v[198:201], v[202:205], v[50:65]
	v_mfma_f32_32x32x16_bf16 v[34:49], v[198:201], v[206:209], v[34:49]
	v_mfma_f32_32x32x16_bf16 v[18:33], v[214:217], v[202:205], v[18:33]
	v_mfma_f32_32x32x16_bf16 v[2:17], v[214:217], v[206:209], v[2:17]
	global_load_dwordx4 v[66:69], v[160:161], off offset:1152
	global_load_dwordx4 v[70:73], v[162:163], off offset:1152
	global_load_dwordx4 v[74:77], v[164:165], off offset:1152
	global_load_dwordx4 v[78:81], v[166:167], off offset:1152
	global_load_dwordx4 v[82:85], v[158:159], off offset:1152
	global_load_dwordx4 v[90:93], v[168:169], off offset:1152
	global_load_dwordx4 v[94:97], v[170:171], off offset:1152
	global_load_dwordx4 v[106:109], v[172:173], off offset:1152
	ds_read_b128 v[198:201], v140 offset:36928
	ds_read_b128 v[202:205], v141 offset:55360
	ds_read_b128 v[206:209], v141 offset:59968
	ds_read_b128 v[214:217], v140 offset:41536
	s_waitcnt lgkmcnt(4)
	v_mfma_f32_32x32x16_bf16 v[50:65], v[218:221], v[222:225], v[50:65]
	v_mfma_f32_32x32x16_bf16 v[34:49], v[218:221], v[226:229], v[34:49]
	v_mfma_f32_32x32x16_bf16 v[18:33], v[230:233], v[222:225], v[18:33]
	v_mfma_f32_32x32x16_bf16 v[2:17], v[230:233], v[226:229], v[2:17]
	s_waitcnt vmcnt(8)
	ds_write_b128 v188, v[86:89]
	ds_write_b128 v188, v[98:101] offset:4608
	ds_write_b128 v188, v[102:105] offset:9216
	ds_write_b128 v188, v[110:113] offset:13824
	ds_read_b128 v[218:221], v140 offset:36960
	ds_read_b128 v[222:225], v141 offset:55392
	ds_read_b128 v[226:229], v141 offset:60000
	ds_read_b128 v[230:233], v140 offset:41568
	s_waitcnt lgkmcnt(4)
	v_mfma_f32_32x32x16_bf16 v[50:65], v[198:201], v[202:205], v[50:65]
	v_mfma_f32_32x32x16_bf16 v[34:49], v[198:201], v[206:209], v[34:49]
	v_mfma_f32_32x32x16_bf16 v[18:33], v[214:217], v[202:205], v[18:33]
	v_mfma_f32_32x32x16_bf16 v[2:17], v[214:217], v[206:209], v[2:17]
	ds_write_b128 v188, v[114:117] offset:18432
	ds_write_b128 v188, v[118:121] offset:23040
	ds_write_b128 v188, v[122:125] offset:27648
	ds_write_b128 v188, v[126:129] offset:32256
	s_waitcnt lgkmcnt(0)
	v_mfma_f32_32x32x16_bf16 v[50:65], v[218:221], v[222:225], v[50:65]
	v_mfma_f32_32x32x16_bf16 v[34:49], v[218:221], v[226:229], v[34:49]
	v_mfma_f32_32x32x16_bf16 v[18:33], v[230:233], v[222:225], v[18:33]
	v_mfma_f32_32x32x16_bf16 v[2:17], v[230:233], v[226:229], v[2:17]
	s_setprio 0
	s_waitcnt lgkmcnt(0)
	s_barrier
	s_setprio 1
	ds_read_b128 v[198:201], v140
	ds_read_b128 v[202:205], v141 offset:18432
	ds_read_b128 v[206:209], v141 offset:23040
	ds_read_b128 v[214:217], v140 offset:4608
	ds_read_b128 v[218:221], v140 offset:32
	ds_read_b128 v[222:225], v141 offset:18464
	ds_read_b128 v[226:229], v141 offset:23072
	ds_read_b128 v[230:233], v140 offset:4640
	s_waitcnt lgkmcnt(4)
	v_mfma_f32_32x32x16_bf16 v[50:65], v[198:201], v[202:205], v[50:65]
	v_mfma_f32_32x32x16_bf16 v[34:49], v[198:201], v[206:209], v[34:49]
	v_mfma_f32_32x32x16_bf16 v[18:33], v[214:217], v[202:205], v[18:33]
	v_mfma_f32_32x32x16_bf16 v[2:17], v[214:217], v[206:209], v[2:17]
	global_load_dwordx4 v[86:89], v[160:161], off offset:1280
	global_load_dwordx4 v[98:101], v[162:163], off offset:1280
	global_load_dwordx4 v[102:105], v[164:165], off offset:1280
	global_load_dwordx4 v[110:113], v[166:167], off offset:1280
	global_load_dwordx4 v[114:117], v[158:159], off offset:1280
	global_load_dwordx4 v[118:121], v[168:169], off offset:1280
	global_load_dwordx4 v[122:125], v[170:171], off offset:1280
	global_load_dwordx4 v[126:129], v[172:173], off offset:1280
	ds_read_b128 v[198:201], v140 offset:64
	ds_read_b128 v[202:205], v141 offset:18496
	ds_read_b128 v[206:209], v141 offset:23104
	ds_read_b128 v[214:217], v140 offset:4672
	s_waitcnt lgkmcnt(4)
	v_mfma_f32_32x32x16_bf16 v[50:65], v[218:221], v[222:225], v[50:65]
	v_mfma_f32_32x32x16_bf16 v[34:49], v[218:221], v[226:229], v[34:49]
	v_mfma_f32_32x32x16_bf16 v[18:33], v[230:233], v[222:225], v[18:33]
	v_mfma_f32_32x32x16_bf16 v[2:17], v[230:233], v[226:229], v[2:17]
	s_waitcnt vmcnt(8)
	ds_write_b128 v188, v[66:69] offset:36864
	ds_write_b128 v188, v[70:73] offset:41472
	ds_write_b128 v188, v[74:77] offset:46080
	ds_write_b128 v188, v[78:81] offset:50688
	ds_read_b128 v[218:221], v140 offset:96
	ds_read_b128 v[222:225], v141 offset:18528
	ds_read_b128 v[226:229], v141 offset:23136
	ds_read_b128 v[230:233], v140 offset:4704
	s_waitcnt lgkmcnt(4)
	v_mfma_f32_32x32x16_bf16 v[50:65], v[198:201], v[202:205], v[50:65]
	v_mfma_f32_32x32x16_bf16 v[34:49], v[198:201], v[206:209], v[34:49]
	v_mfma_f32_32x32x16_bf16 v[18:33], v[214:217], v[202:205], v[18:33]
	v_mfma_f32_32x32x16_bf16 v[2:17], v[214:217], v[206:209], v[2:17]
	ds_write_b128 v188, v[82:85] offset:55296
	ds_write_b128 v188, v[90:93] offset:59904
	ds_write_b128 v188, v[94:97] offset:64512
	ds_write_b128 v189, v[106:109] offset:13824
	s_waitcnt lgkmcnt(0)
	v_mfma_f32_32x32x16_bf16 v[50:65], v[218:221], v[222:225], v[50:65]
	v_mfma_f32_32x32x16_bf16 v[34:49], v[218:221], v[226:229], v[34:49]
	v_mfma_f32_32x32x16_bf16 v[18:33], v[230:233], v[222:225], v[18:33]
	v_mfma_f32_32x32x16_bf16 v[2:17], v[230:233], v[226:229], v[2:17]
	s_setprio 0
	s_waitcnt lgkmcnt(0)
	s_barrier
; __device__ __forceinline__ void gemm_kstep(const u16* sb, int wn, int wt, int r, int h, f32x16 (&acc)[2][2]) {
;   const u16* bw = sb + (wn * 64 + r) * LDT + h * 8;
;   const u16* bx = sb + TILE_U16 + (wt * 64 + r) * LDT + h * 8;
;   __builtin_amdgcn_s_setprio(1);
; #pragma unroll
;   for (int ks = 0; ks < 4; ++ks) {
;     bf16x8 a0 = *(const bf16x8*)(bw + ks * 16);
;     bf16x8 a1 = *(const bf16x8*)(bw + 32 * LDT + ks * 16);
;     bf16x8 b0 = *(const bf16x8*)(bx + ks * 16);
;     bf16x8 b1 = *(const bf16x8*)(bx + 32 * LDT + ks * 16);
;     acc[0][0] = mfma32(a0, b0, acc[0][0]);
;     acc[0][1] = mfma32(a0, b1, acc[0][1]);
;     acc[1][0] = mfma32(a1, b0, acc[1][0]);
;     acc[1][1] = mfma32(a1, b1, acc[1][1]);
;   }
;   __builtin_amdgcn_s_setprio(0);
; }
; __device__ void gemm_phase(const u16* __restrict__ Wb, int ldw, const u16* __restrict__ Xb, int ldx, int K,
;                            u16* __restrict__ outb, int ldo, int ntn, int ntiles, u16* lds) {
;     ...
;     for (int kt = 0; kt < nk; kt += 2) {
;       if (kt + 2 < nk) gs_load(B, gw, ldw, gx, ldx, (kt + 2) * 64);
;       else if (has_next) gs_load(B, gwn, ldw, gxn, ldx, 0);
;       gemm_kstep(lds, wn, wt, r, h, acc);
;       gs_store(A, lds + 2 * TILE_U16, lo);
;       __syncthreads();
;       if (kt + 3 < nk) gs_load(A, gw, ldw, gx, ldx, (kt + 3) * 64);
;       else if (has_next) gs_load(A, gwn, ldw, gxn, ldx, 64);
;       gemm_kstep(lds + 2 * TILE_U16, wn, wt, r, h, acc);
;       if (kt + 2 < nk) gs_store(B, lds, lo);
;       __syncthreads();
;     }
	s_setprio 1
	ds_read_b128 v[198:201], v140 offset:36864
	ds_read_b128 v[202:205], v141 offset:55296
	ds_read_b128 v[206:209], v141 offset:59904
	ds_read_b128 v[214:217], v140 offset:41472
	ds_read_b128 v[218:221], v140 offset:36896
	ds_read_b128 v[222:225], v141 offset:55328
	ds_read_b128 v[226:229], v141 offset:59936
	ds_read_b128 v[230:233], v140 offset:41504
	s_waitcnt lgkmcnt(4)
	v_mfma_f32_32x32x16_bf16 v[50:65], v[198:201], v[202:205], v[50:65]
	v_mfma_f32_32x32x16_bf16 v[34:49], v[198:201], v[206:209], v[34:49]
	v_mfma_f32_32x32x16_bf16 v[18:33], v[214:217], v[202:205], v[18:33]
	v_mfma_f32_32x32x16_bf16 v[2:17], v[214:217], v[206:209], v[2:17]
	global_load_dwordx4 v[66:69], v[160:161], off offset:1408
	global_load_dwordx4 v[70:73], v[162:163], off offset:1408
	global_load_dwordx4 v[74:77], v[164:165], off offset:1408
	global_load_dwordx4 v[78:81], v[166:167], off offset:1408
	global_load_dwordx4 v[82:85], v[158:159], off offset:1408
	global_load_dwordx4 v[90:93], v[168:169], off offset:1408
	global_load_dwordx4 v[94:97], v[170:171], off offset:1408
	global_load_dwordx4 v[106:109], v[172:173], off offset:1408
	ds_read_b128 v[198:201], v140 offset:36928
	ds_read_b128 v[202:205], v141 offset:55360
	ds_read_b128 v[206:209], v141 offset:59968
	ds_read_b128 v[214:217], v140 offset:41536
	s_waitcnt lgkmcnt(4)
	v_mfma_f32_32x32x16_bf16 v[50:65], v[218:221], v[222:225], v[50:65]
	v_mfma_f32_32x32x16_bf16 v[34:49], v[218:221], v[226:229], v[34:49]
	v_mfma_f32_32x32x16_bf16 v[18:33], v[230:233], v[222:225], v[18:33]
	v_mfma_f32_32x32x16_bf16 v[2:17], v[230:233], v[226:229], v[2:17]
	s_waitcnt vmcnt(8)
	ds_write_b128 v188, v[86:89]
	ds_write_b128 v188, v[98:101] offset:4608
	ds_write_b128 v188, v[102:105] offset:9216
	ds_write_b128 v188, v[110:113] offset:13824
	ds_read_b128 v[218:221], v140 offset:36960
	ds_read_b128 v[222:225], v141 offset:55392
	ds_read_b128 v[226:229], v141 offset:60000
	ds_read_b128 v[230:233], v140 offset:41568
	s_waitcnt lgkmcnt(4)
	v_mfma_f32_32x32x16_bf16 v[50:65], v[198:201], v[202:205], v[50:65]
	v_mfma_f32_32x32x16_bf16 v[34:49], v[198:201], v[206:209], v[34:49]
	v_mfma_f32_32x32x16_bf16 v[18:33], v[214:217], v[202:205], v[18:33]
	v_mfma_f32_32x32x16_bf16 v[2:17], v[214:217], v[206:209], v[2:17]
	ds_write_b128 v188, v[114:117] offset:18432
	ds_write_b128 v188, v[118:121] offset:23040
	ds_write_b128 v188, v[122:125] offset:27648
	ds_write_b128 v188, v[126:129] offset:32256
	s_waitcnt lgkmcnt(0)
	v_mfma_f32_32x32x16_bf16 v[50:65], v[218:221], v[222:225], v[50:65]
	v_mfma_f32_32x32x16_bf16 v[34:49], v[218:221], v[226:229], v[34:49]
	v_mfma_f32_32x32x16_bf16 v[18:33], v[230:233], v[222:225], v[18:33]
	v_mfma_f32_32x32x16_bf16 v[2:17], v[230:233], v[226:229], v[2:17]
	s_setprio 0
	s_waitcnt lgkmcnt(0)
	s_barrier
	s_setprio 1
	ds_read_b128 v[198:201], v140
	ds_read_b128 v[202:205], v141 offset:18432
	ds_read_b128 v[206:209], v141 offset:23040
	ds_read_b128 v[214:217], v140 offset:4608
	ds_read_b128 v[218:221], v140 offset:32
	ds_read_b128 v[222:225], v141 offset:18464
	ds_read_b128 v[226:229], v141 offset:23072
	ds_read_b128 v[230:233], v140 offset:4640
	s_waitcnt lgkmcnt(4)
	v_mfma_f32_32x32x16_bf16 v[50:65], v[198:201], v[202:205], v[50:65]
	v_mfma_f32_32x32x16_bf16 v[34:49], v[198:201], v[206:209], v[34:49]
	v_mfma_f32_32x32x16_bf16 v[18:33], v[214:217], v[202:205], v[18:33]
	v_mfma_f32_32x32x16_bf16 v[2:17], v[214:217], v[206:209], v[2:17]
	global_load_dwordx4 v[86:89], v[160:161], off offset:1536
	global_load_dwordx4 v[98:101], v[162:163], off offset:1536
	global_load_dwordx4 v[102:105], v[164:165], off offset:1536
	global_load_dwordx4 v[110:113], v[166:167], off offset:1536
	global_load_dwordx4 v[114:117], v[158:159], off offset:1536
	global_load_dwordx4 v[118:121], v[168:169], off offset:1536
	global_load_dwordx4 v[122:125], v[170:171], off offset:1536
	global_load_dwordx4 v[126:129], v[172:173], off offset:1536
	ds_read_b128 v[198:201], v140 offset:64
	ds_read_b128 v[202:205], v141 offset:18496
	ds_read_b128 v[206:209], v141 offset:23104
	ds_read_b128 v[214:217], v140 offset:4672
	s_waitcnt lgkmcnt(4)
	v_mfma_f32_32x32x16_bf16 v[50:65], v[218:221], v[222:225], v[50:65]
	v_mfma_f32_32x32x16_bf16 v[34:49], v[218:221], v[226:229], v[34:49]
	v_mfma_f32_32x32x16_bf16 v[18:33], v[230:233], v[222:225], v[18:33]
	v_mfma_f32_32x32x16_bf16 v[2:17], v[230:233], v[226:229], v[2:17]
	s_waitcnt vmcnt(8)
	ds_write_b128 v188, v[66:69] offset:36864
	ds_write_b128 v188, v[70:73] offset:41472
	ds_write_b128 v188, v[74:77] offset:46080
	ds_write_b128 v188, v[78:81] offset:50688
	ds_read_b128 v[218:221], v140 offset:96
	ds_read_b128 v[222:225], v141 offset:18528
	ds_read_b128 v[226:229], v141 offset:23136
	ds_read_b128 v[230:233], v140 offset:4704
	s_waitcnt lgkmcnt(4)
	v_mfma_f32_32x32x16_bf16 v[50:65], v[198:201], v[202:205], v[50:65]
	v_mfma_f32_32x32x16_bf16 v[34:49], v[198:201], v[206:209], v[34:49]
	v_mfma_f32_32x32x16_bf16 v[18:33], v[214:217], v[202:205], v[18:33]
	v_mfma_f32_32x32x16_bf16 v[2:17], v[214:217], v[206:209], v[2:17]
	ds_write_b128 v188, v[82:85] offset:55296
	ds_write_b128 v188, v[90:93] offset:59904
	ds_write_b128 v188, v[94:97] offset:64512
	ds_write_b128 v189, v[106:109] offset:13824
	s_waitcnt lgkmcnt(0)
	v_mfma_f32_32x32x16_bf16 v[50:65], v[218:221], v[222:225], v[50:65]
	v_mfma_f32_32x32x16_bf16 v[34:49], v[218:221], v[226:229], v[34:49]
	v_mfma_f32_32x32x16_bf16 v[18:33], v[230:233], v[222:225], v[18:33]
	v_mfma_f32_32x32x16_bf16 v[2:17], v[230:233], v[226:229], v[2:17]
	s_setprio 0
	s_waitcnt lgkmcnt(0)
	s_barrier
; __device__ __forceinline__ void gemm_kstep(const u16* sb, int wn, int wt, int r, int h, f32x16 (&acc)[2][2]) {
;   const u16* bw = sb + (wn * 64 + r) * LDT + h * 8;
;   const u16* bx = sb + TILE_U16 + (wt * 64 + r) * LDT + h * 8;
;   __builtin_amdgcn_s_setprio(1);
; #pragma unroll
;   for (int ks = 0; ks < 4; ++ks) {
;     bf16x8 a0 = *(const bf16x8*)(bw + ks * 16);
;     bf16x8 a1 = *(const bf16x8*)(bw + 32 * LDT + ks * 16);
;     bf16x8 b0 = *(const bf16x8*)(bx + ks * 16);
;     bf16x8 b1 = *(const bf16x8*)(bx + 32 * LDT + ks * 16);
;     acc[0][0] = mfma32(a0, b0, acc[0][0]);
;     acc[0][1] = mfma32(a0, b1, acc[0][1]);
;     acc[1][0] = mfma32(a1, b0, acc[1][0]);
;     acc[1][1] = mfma32(a1, b1, acc[1][1]);
;   }
;   __builtin_amdgcn_s_setprio(0);
; }
; __device__ void gemm_phase(const u16* __restrict__ Wb, int ldw, const u16* __restrict__ Xb, int ldx, int K,
;                            u16* __restrict__ outb, int ldo, int ntn, int ntiles, u16* lds) {
;     ...
;     for (int kt = 0; kt < nk; kt += 2) {
;       if (kt + 2 < nk) gs_load(B, gw, ldw, gx, ldx, (kt + 2) * 64);
;       else if (has_next) gs_load(B, gwn, ldw, gxn, ldx, 0);
;       gemm_kstep(lds, wn, wt, r, h, acc);
;       gs_store(A, lds + 2 * TILE_U16, lo);
;       __syncthreads();
;       if (kt + 3 < nk) gs_load(A, gw, ldw, gx, ldx, (kt + 3) * 64);
;       else if (has_next) gs_load(A, gwn, ldw, gxn, ldx, 64);
;       gemm_kstep(lds + 2 * TILE_U16, wn, wt, r, h, acc);
;       if (kt + 2 < nk) gs_store(B, lds, lo);
;       __syncthreads();
;     }
	s_setprio 1
	ds_read_b128 v[198:201], v140 offset:36864
	ds_read_b128 v[202:205], v141 offset:55296
	ds_read_b128 v[206:209], v141 offset:59904
	ds_read_b128 v[214:217], v140 offset:41472
	ds_read_b128 v[218:221], v140 offset:36896
	ds_read_b128 v[222:225], v141 offset:55328
	ds_read_b128 v[226:229], v141 offset:59936
	ds_read_b128 v[230:233], v140 offset:41504
	s_waitcnt lgkmcnt(4)
	v_mfma_f32_32x32x16_bf16 v[50:65], v[198:201], v[202:205], v[50:65]
	v_mfma_f32_32x32x16_bf16 v[34:49], v[198:201], v[206:209], v[34:49]
	v_mfma_f32_32x32x16_bf16 v[18:33], v[214:217], v[202:205], v[18:33]
	v_mfma_f32_32x32x16_bf16 v[2:17], v[214:217], v[206:209], v[2:17]
	global_load_dwordx4 v[66:69], v[160:161], off offset:1664
	global_load_dwordx4 v[70:73], v[162:163], off offset:1664
	global_load_dwordx4 v[74:77], v[164:165], off offset:1664
	global_load_dwordx4 v[78:81], v[166:167], off offset:1664
	global_load_dwordx4 v[82:85], v[158:159], off offset:1664
	global_load_dwordx4 v[90:93], v[168:169], off offset:1664
	global_load_dwordx4 v[94:97], v[170:171], off offset:1664
	global_load_dwordx4 v[106:109], v[172:173], off offset:1664
	ds_read_b128 v[198:201], v140 offset:36928
	ds_read_b128 v[202:205], v141 offset:55360
	ds_read_b128 v[206:209], v141 offset:59968
	ds_read_b128 v[214:217], v140 offset:41536
	s_waitcnt lgkmcnt(4)
	v_mfma_f32_32x32x16_bf16 v[50:65], v[218:221], v[222:225], v[50:65]
	v_mfma_f32_32x32x16_bf16 v[34:49], v[218:221], v[226:229], v[34:49]
	v_mfma_f32_32x32x16_bf16 v[18:33], v[230:233], v[222:225], v[18:33]
	v_mfma_f32_32x32x16_bf16 v[2:17], v[230:233], v[226:229], v[2:17]
	s_waitcnt vmcnt(8)
	ds_write_b128 v188, v[86:89]
	ds_write_b128 v188, v[98:101] offset:4608
	ds_write_b128 v188, v[102:105] offset:9216
	ds_write_b128 v188, v[110:113] offset:13824
	ds_read_b128 v[218:221], v140 offset:36960
	ds_read_b128 v[222:225], v141 offset:55392
	ds_read_b128 v[226:229], v141 offset:60000
	ds_read_b128 v[230:233], v140 offset:41568
	s_waitcnt lgkmcnt(4)
	v_mfma_f32_32x32x16_bf16 v[50:65], v[198:201], v[202:205], v[50:65]
	v_mfma_f32_32x32x16_bf16 v[34:49], v[198:201], v[206:209], v[34:49]
	v_mfma_f32_32x32x16_bf16 v[18:33], v[214:217], v[202:205], v[18:33]
	v_mfma_f32_32x32x16_bf16 v[2:17], v[214:217], v[206:209], v[2:17]
	ds_write_b128 v188, v[114:117] offset:18432
	ds_write_b128 v188, v[118:121] offset:23040
	ds_write_b128 v188, v[122:125] offset:27648
	ds_write_b128 v188, v[126:129] offset:32256
	s_waitcnt lgkmcnt(0)
	v_mfma_f32_32x32x16_bf16 v[50:65], v[218:221], v[222:225], v[50:65]
	v_mfma_f32_32x32x16_bf16 v[34:49], v[218:221], v[226:229], v[34:49]
	v_mfma_f32_32x32x16_bf16 v[18:33], v[230:233], v[222:225], v[18:33]
	v_mfma_f32_32x32x16_bf16 v[2:17], v[230:233], v[226:229], v[2:17]
	s_setprio 0
	s_waitcnt lgkmcnt(0)
	s_barrier
	s_setprio 1
	ds_read_b128 v[198:201], v140
	ds_read_b128 v[202:205], v141 offset:18432
	ds_read_b128 v[206:209], v141 offset:23040
	ds_read_b128 v[214:217], v140 offset:4608
	ds_read_b128 v[218:221], v140 offset:32
	ds_read_b128 v[222:225], v141 offset:18464
	ds_read_b128 v[226:229], v141 offset:23072
	ds_read_b128 v[230:233], v140 offset:4640
	s_waitcnt lgkmcnt(4)
	v_mfma_f32_32x32x16_bf16 v[50:65], v[198:201], v[202:205], v[50:65]
	v_mfma_f32_32x32x16_bf16 v[34:49], v[198:201], v[206:209], v[34:49]
	v_mfma_f32_32x32x16_bf16 v[18:33], v[214:217], v[202:205], v[18:33]
	v_mfma_f32_32x32x16_bf16 v[2:17], v[214:217], v[206:209], v[2:17]
	global_load_dwordx4 v[86:89], v[160:161], off offset:1792
	global_load_dwordx4 v[98:101], v[162:163], off offset:1792
	global_load_dwordx4 v[102:105], v[164:165], off offset:1792
	global_load_dwordx4 v[110:113], v[166:167], off offset:1792
	global_load_dwordx4 v[114:117], v[158:159], off offset:1792
	global_load_dwordx4 v[118:121], v[168:169], off offset:1792
	global_load_dwordx4 v[122:125], v[170:171], off offset:1792
	global_load_dwordx4 v[126:129], v[172:173], off offset:1792
	ds_read_b128 v[198:201], v140 offset:64
	ds_read_b128 v[202:205], v141 offset:18496
	ds_read_b128 v[206:209], v141 offset:23104
	ds_read_b128 v[214:217], v140 offset:4672
	s_waitcnt lgkmcnt(4)
	v_mfma_f32_32x32x16_bf16 v[50:65], v[218:221], v[222:225], v[50:65]
	v_mfma_f32_32x32x16_bf16 v[34:49], v[218:221], v[226:229], v[34:49]
	v_mfma_f32_32x32x16_bf16 v[18:33], v[230:233], v[222:225], v[18:33]
	v_mfma_f32_32x32x16_bf16 v[2:17], v[230:233], v[226:229], v[2:17]
	s_waitcnt vmcnt(8)
	ds_write_b128 v188, v[66:69] offset:36864
	ds_write_b128 v188, v[70:73] offset:41472
	ds_write_b128 v188, v[74:77] offset:46080
	ds_write_b128 v188, v[78:81] offset:50688
	ds_read_b128 v[218:221], v140 offset:96
	ds_read_b128 v[222:225], v141 offset:18528
	ds_read_b128 v[226:229], v141 offset:23136
	ds_read_b128 v[230:233], v140 offset:4704
	s_waitcnt lgkmcnt(4)
	v_mfma_f32_32x32x16_bf16 v[50:65], v[198:201], v[202:205], v[50:65]
	v_mfma_f32_32x32x16_bf16 v[34:49], v[198:201], v[206:209], v[34:49]
	v_mfma_f32_32x32x16_bf16 v[18:33], v[214:217], v[202:205], v[18:33]
	v_mfma_f32_32x32x16_bf16 v[2:17], v[214:217], v[206:209], v[2:17]
	ds_write_b128 v188, v[82:85] offset:55296
	ds_write_b128 v188, v[90:93] offset:59904
	ds_write_b128 v188, v[94:97] offset:64512
	ds_write_b128 v189, v[106:109] offset:13824
	s_waitcnt lgkmcnt(0)
	v_mfma_f32_32x32x16_bf16 v[50:65], v[218:221], v[222:225], v[50:65]
	v_mfma_f32_32x32x16_bf16 v[34:49], v[218:221], v[226:229], v[34:49]
	v_mfma_f32_32x32x16_bf16 v[18:33], v[230:233], v[222:225], v[18:33]
	v_mfma_f32_32x32x16_bf16 v[2:17], v[230:233], v[226:229], v[2:17]
	s_setprio 0
	s_waitcnt lgkmcnt(0)
	s_barrier
; __device__ __forceinline__ void gemm_kstep(const u16* sb, int wn, int wt, int r, int h, f32x16 (&acc)[2][2]) {
;   const u16* bw = sb + (wn * 64 + r) * LDT + h * 8;
;   const u16* bx = sb + TILE_U16 + (wt * 64 + r) * LDT + h * 8;
;   __builtin_amdgcn_s_setprio(1);
; #pragma unroll
;   for (int ks = 0; ks < 4; ++ks) {
;     bf16x8 a0 = *(const bf16x8*)(bw + ks * 16);
;     bf16x8 a1 = *(const bf16x8*)(bw + 32 * LDT + ks * 16);
;     bf16x8 b0 = *(const bf16x8*)(bx + ks * 16);
;     bf16x8 b1 = *(const bf16x8*)(bx + 32 * LDT + ks * 16);
;     acc[0][0] = mfma32(a0, b0, acc[0][0]);
;     acc[0][1] = mfma32(a0, b1, acc[0][1]);
;     acc[1][0] = mfma32(a1, b0, acc[1][0]);
;     acc[1][1] = mfma32(a1, b1, acc[1][1]);
;   }
;   __builtin_amdgcn_s_setprio(0);
; }
; __device__ void gemm_phase(const u16* __restrict__ Wb, int ldw, const u16* __restrict__ Xb, int ldx, int K,
;                            u16* __restrict__ outb, int ldo, int ntn, int ntiles, u16* lds) {
;     ...
;     for (int kt = 0; kt < nk; kt += 2) {
;       if (kt + 2 < nk) gs_load(B, gw, ldw, gx, ldx, (kt + 2) * 64);
;       else if (has_next) gs_load(B, gwn, ldw, gxn, ldx, 0);
	global_load_dwordx4 v[66:69], v[160:161], off offset:1920
	global_load_dwordx4 v[70:73], v[162:163], off offset:1920
	global_load_dwordx4 v[74:77], v[164:165], off offset:1920
	global_load_dwordx4 v[78:81], v[166:167], off offset:1920
	global_load_dwordx4 v[82:85], v[158:159], off offset:1920
	global_load_dwordx4 v[90:93], v[168:169], off offset:1920
	global_load_dwordx4 v[94:97], v[170:171], off offset:1920
	global_load_dwordx4 v[106:109], v[172:173], off offset:1920
	s_setprio 1
	ds_read_b128 v[158:161], v140 offset:36864
	ds_read_b128 v[162:165], v141 offset:55296
	ds_read_b128 v[166:169], v141 offset:59904
	ds_read_b128 v[214:217], v140 offset:41472
	ds_read_b128 v[218:221], v140 offset:36896
	ds_read_b128 v[222:225], v141 offset:55328
	ds_read_b128 v[226:229], v141 offset:59936
	ds_read_b128 v[230:233], v140 offset:41504
	s_waitcnt lgkmcnt(4)
	v_mfma_f32_32x32x16_bf16 v[50:65], v[158:161], v[162:165], v[50:65]
	v_mfma_f32_32x32x16_bf16 v[34:49], v[158:161], v[166:169], v[34:49]
	v_mfma_f32_32x32x16_bf16 v[18:33], v[214:217], v[162:165], v[18:33]
	v_mfma_f32_32x32x16_bf16 v[2:17], v[214:217], v[166:169], v[2:17]
	ds_read_b128 v[158:161], v140 offset:36928
	ds_read_b128 v[162:165], v141 offset:55360
	ds_read_b128 v[166:169], v141 offset:59968
	ds_read_b128 v[214:217], v140 offset:41536
	s_waitcnt lgkmcnt(4)
	v_mfma_f32_32x32x16_bf16 v[50:65], v[218:221], v[222:225], v[50:65]
	v_mfma_f32_32x32x16_bf16 v[34:49], v[218:221], v[226:229], v[34:49]
	v_mfma_f32_32x32x16_bf16 v[18:33], v[230:233], v[222:225], v[18:33]
	v_mfma_f32_32x32x16_bf16 v[2:17], v[230:233], v[226:229], v[2:17]
	ds_read_b128 v[218:221], v140 offset:36960
	ds_read_b128 v[222:225], v141 offset:55392
	ds_read_b128 v[226:229], v141 offset:60000
	ds_read_b128 v[230:233], v140 offset:41568
	s_waitcnt lgkmcnt(4)
	v_mfma_f32_32x32x16_bf16 v[50:65], v[158:161], v[162:165], v[50:65]
	v_mfma_f32_32x32x16_bf16 v[34:49], v[158:161], v[166:169], v[34:49]
	v_mfma_f32_32x32x16_bf16 v[18:33], v[214:217], v[162:165], v[18:33]
	v_mfma_f32_32x32x16_bf16 v[2:17], v[214:217], v[166:169], v[2:17]
	s_waitcnt lgkmcnt(0)
	v_mfma_f32_32x32x16_bf16 v[50:65], v[218:221], v[222:225], v[50:65]
	v_mfma_f32_32x32x16_bf16 v[34:49], v[218:221], v[226:229], v[34:49]
	v_mfma_f32_32x32x16_bf16 v[18:33], v[230:233], v[222:225], v[18:33]
	v_mfma_f32_32x32x16_bf16 v[2:17], v[230:233], v[226:229], v[2:17]
	s_setprio 0
	s_and_b64 vcc, exec, s[0:1]
	s_waitcnt vmcnt(8)
	ds_write_b128 v188, v[86:89]
	ds_write_b128 v188, v[98:101] offset:4608
	ds_write_b128 v188, v[102:105] offset:9216
	ds_write_b128 v188, v[110:113] offset:13824
	ds_write_b128 v188, v[114:117] offset:18432
	ds_write_b128 v188, v[118:121] offset:23040
	ds_write_b128 v188, v[122:125] offset:27648
	ds_write_b128 v188, v[126:129] offset:32256
	s_waitcnt lgkmcnt(0)
	s_barrier
	s_cbranch_vccnz .LBB0_611
	v_add_co_u32_e32 v98, vcc, 0x10000, v132
	global_load_dwordx4 v[86:89], v[132:133], off
	s_nop 0
	v_addc_co_u32_e32 v99, vcc, 0, v133, vcc
	v_add_co_u32_e32 v102, vcc, 0x20000, v132
	s_nop 1
	v_addc_co_u32_e32 v103, vcc, 0, v133, vcc
	v_add_co_u32_e32 v110, vcc, 0x30000, v132
	global_load_dwordx4 v[98:101], v[98:99], off
	s_nop 0
	global_load_dwordx4 v[102:105], v[102:103], off
	v_addc_co_u32_e32 v111, vcc, 0, v133, vcc
	v_add_co_u32_e32 v118, vcc, 0x10000, v134
	global_load_dwordx4 v[110:113], v[110:111], off
	s_nop 0
	global_load_dwordx4 v[114:117], v[134:135], off
	v_addc_co_u32_e32 v119, vcc, 0, v135, vcc
	v_add_co_u32_e32 v122, vcc, 0x20000, v134
	s_nop 1
	v_addc_co_u32_e32 v123, vcc, 0, v135, vcc
	v_add_co_u32_e32 v126, vcc, 0x30000, v134
	global_load_dwordx4 v[118:121], v[118:119], off
	s_nop 0
	global_load_dwordx4 v[122:125], v[122:123], off
	v_addc_co_u32_e32 v127, vcc, 0, v135, vcc
	global_load_dwordx4 v[126:129], v[126:127], off
